# all GEMM k-loops: fragment ds_reads issued first, staging ds_writes and next loads moved under the tail of each half MFMA block
# baseline (speedup 1.0000x reference)
; DI f32x4 mfma16(bf16x8 a, bf16x8 b, f32x4 c) { return __builtin_amdgcn_mfma_f32_16x16x32_bf16(a, b, c, 0, 0, 0); }
; #pragma unroll
;   for (int ks = KS0; ks < KS1; ++ks) {
;     bf16x8 af[8], bfr[4];
; #pragma unroll
;     for (int i = 0; i < 8; ++i) {
;       const int r = wm * 128 + i * 16 + (lane & 15);
;       af[i] = *(const bf16x8*)(S + r * 64 + (((ks * 4 + (lane >> 4)) ^ ((r >> 1) & 7)) << 3));
;     }
; #pragma unroll
;     for (int j = 0; j < 4; ++j) {
;       const int r = wn * 64 + j * 16 + (lane & 15);
;       bfr[j] = *(const bf16x8*)(S + 16384 + r * 64 + (((ks * 4 + (lane >> 4)) ^ ((r >> 1) & 7)) << 3));
;     }
;     __builtin_amdgcn_s_setprio(1);
; #pragma unroll
;     for (int i = 0; i < 8; ++i)
; #pragma unroll
;       for (int j = 0; j < 4; ++j) acc[i][j] = mfma16(bfr[j], af[i], acc[i][j]);
;     __builtin_amdgcn_s_setprio(0);
;   }
; }
; DI void gemm8_accum(f32x4 (&acc)[8][4], const bf16_t* a, size_t lda, const bf16_t* b, size_t ldb, int nkb, bf16_t* L,
;                     const bool pre, const bf16_t* an, size_t ldan, const bf16_t* bn, size_t ldbn) {
;     ...
;   for (int kb = 0; kb + 2 < nkb; ++kb) {
;     __syncthreads();
;     g8_store1(L + ((kb + 1) & 1) * 32768, ra, lrow, lch);
;     g8_load1o(ra, a + (kb + 2) * 64, offa);
;     __builtin_amdgcn_sched_barrier(0);
;     g8_compute<0, 1>(acc, L + (kb & 1) * 32768, wm, wn, lane);
;     __builtin_amdgcn_sched_barrier(0);
;     g8_store1(L + ((kb + 1) & 1) * 32768 + 16384, rb, lrow, lch);
;     g8_load1o(rb, b + (kb + 2) * 64, offb);
;     __builtin_amdgcn_sched_barrier(0);
;     g8_compute<1, 2>(acc, L + (kb & 1) * 32768, wm, wn, lane);
;   }
.LBB0_134:
	s_add_i32 s3, s2, 0x8000
	s_and_b32 s6, s3, 0x8000
	v_lshl_add_u32 v167, s6, 1, v163
	v_lshl_add_u32 v199, s6, 1, v163
	s_waitcnt lgkmcnt(0)
	s_barrier
	s_cmp_eq_u32 s100, 0
	s_cbranch_scc1 .Lstg_134_a
	s_setprio 1
	v_mfma_f32_16x16x32_bf16 v[34:37], v[234:237], v[192:195], v[34:37]
	v_mfma_f32_16x16x32_bf16 v[38:41], v[238:241], v[192:195], v[38:41]
	v_mfma_f32_16x16x32_bf16 v[42:45], v[242:245], v[192:195], v[42:45]
	v_mfma_f32_16x16x32_bf16 v[46:49], v[246:249], v[192:195], v[46:49]
	v_mfma_f32_16x16x32_bf16 v[50:53], v[234:237], v[206:209], v[50:53]
	v_mfma_f32_16x16x32_bf16 v[54:57], v[238:241], v[206:209], v[54:57]
	v_mfma_f32_16x16x32_bf16 v[58:61], v[242:245], v[206:209], v[58:61]
	v_mfma_f32_16x16x32_bf16 v[62:65], v[246:249], v[206:209], v[62:65]
	v_mfma_f32_16x16x32_bf16 v[66:69], v[234:237], v[210:213], v[66:69]
	v_mfma_f32_16x16x32_bf16 v[70:73], v[238:241], v[210:213], v[70:73]
	v_mfma_f32_16x16x32_bf16 v[74:77], v[242:245], v[210:213], v[74:77]
	v_mfma_f32_16x16x32_bf16 v[78:81], v[246:249], v[210:213], v[78:81]
	v_mfma_f32_16x16x32_bf16 v[82:85], v[234:237], v[214:217], v[82:85]
	v_mfma_f32_16x16x32_bf16 v[86:89], v[238:241], v[214:217], v[86:89]
	v_mfma_f32_16x16x32_bf16 v[90:93], v[242:245], v[214:217], v[90:93]
	v_mfma_f32_16x16x32_bf16 v[94:97], v[246:249], v[214:217], v[94:97]
	v_mfma_f32_16x16x32_bf16 v[98:101], v[234:237], v[218:221], v[98:101]
	v_mfma_f32_16x16x32_bf16 v[102:105], v[238:241], v[218:221], v[102:105]
	v_mfma_f32_16x16x32_bf16 v[106:109], v[242:245], v[218:221], v[106:109]
	v_mfma_f32_16x16x32_bf16 v[110:113], v[246:249], v[218:221], v[110:113]
	v_mfma_f32_16x16x32_bf16 v[114:117], v[234:237], v[222:225], v[114:117]
	v_mfma_f32_16x16x32_bf16 v[118:121], v[238:241], v[222:225], v[118:121]
	v_mfma_f32_16x16x32_bf16 v[122:125], v[242:245], v[222:225], v[122:125]
	v_mfma_f32_16x16x32_bf16 v[126:129], v[246:249], v[222:225], v[126:129]
	v_mfma_f32_16x16x32_bf16 v[130:133], v[234:237], v[226:229], v[130:133]
	v_mfma_f32_16x16x32_bf16 v[134:137], v[238:241], v[226:229], v[134:137]
	v_mfma_f32_16x16x32_bf16 v[138:141], v[242:245], v[226:229], v[138:141]
	v_mfma_f32_16x16x32_bf16 v[142:145], v[246:249], v[226:229], v[142:145]
	v_mfma_f32_16x16x32_bf16 v[146:149], v[234:237], v[230:233], v[146:149]
	v_mfma_f32_16x16x32_bf16 v[150:153], v[238:241], v[230:233], v[150:153]
	v_mfma_f32_16x16x32_bf16 v[154:157], v[242:245], v[230:233], v[154:157]
	v_mfma_f32_16x16x32_bf16 v[158:161], v[246:249], v[230:233], v[158:161]
	s_setprio 0
.Lstg_134_a:
	s_and_b32 s2, s2, 0x8000
	s_lshl_b32 s2, s2, 1
	s_add_i32 s2, s2, 0
	v_lshl_add_u32 v169, v191, 1, s2
	v_add_u32_e32 v198, v169, v187
	ds_read_b128 v[192:195], v198
	ds_read_b128 v[206:209], v198 offset:2048
	ds_read_b128 v[210:213], v198 offset:4096
	ds_read_b128 v[214:217], v198 offset:6144
	ds_read_b128 v[218:221], v198 offset:8192
	ds_read_b128 v[222:225], v198 offset:10240
	ds_read_b128 v[226:229], v198 offset:12288
	ds_read_b128 v[230:233], v198 offset:14336
	v_add_u32_e32 v169, v169, v186
	ds_read_b128 v[234:237], v169 offset:32768
	ds_read_b128 v[238:241], v169 offset:34816
	ds_read_b128 v[242:245], v169 offset:36864
	ds_read_b128 v[246:249], v169 offset:38912
	s_setprio 1
	s_waitcnt lgkmcnt(3)
	v_mfma_f32_16x16x32_bf16 v[34:37], v[234:237], v[192:195], v[34:37]
	s_waitcnt lgkmcnt(2)
	v_mfma_f32_16x16x32_bf16 v[38:41], v[238:241], v[192:195], v[38:41]
	s_waitcnt lgkmcnt(1)
	v_mfma_f32_16x16x32_bf16 v[42:45], v[242:245], v[192:195], v[42:45]
	s_waitcnt lgkmcnt(0)
	s_waitcnt vmcnt(5)
	ds_write_b128 v167, v[22:25]
	ds_write_b128 v167, v[18:21] offset:8192
	ds_write_b128 v167, v[26:29] offset:16384
	s_waitcnt vmcnt(4)
	ds_write_b128 v167, v[30:33] offset:24576
	v_lshl_add_u64 v[18:19], v[184:185], 0, s[0:1]
	v_lshl_add_u64 v[26:27], v[180:181], 0, s[0:1]
	global_load_dwordx4 v[22:25], v[18:19], off
	v_lshl_add_u64 v[30:31], v[178:179], 0, s[0:1]
	global_load_dwordx4 v[26:29], v[26:27], off
	v_lshl_add_u64 v[18:19], v[182:183], 0, s[0:1]
	global_load_dwordx4 v[18:21], v[18:19], off
	s_nop 0
	global_load_dwordx4 v[30:33], v[30:31], off
	v_mfma_f32_16x16x32_bf16 v[46:49], v[246:249], v[192:195], v[46:49]
	v_mfma_f32_16x16x32_bf16 v[50:53], v[234:237], v[206:209], v[50:53]
	v_mfma_f32_16x16x32_bf16 v[54:57], v[238:241], v[206:209], v[54:57]
	v_mfma_f32_16x16x32_bf16 v[58:61], v[242:245], v[206:209], v[58:61]
	v_mfma_f32_16x16x32_bf16 v[62:65], v[246:249], v[206:209], v[62:65]
	v_mfma_f32_16x16x32_bf16 v[66:69], v[234:237], v[210:213], v[66:69]
	v_mfma_f32_16x16x32_bf16 v[70:73], v[238:241], v[210:213], v[70:73]
	v_mfma_f32_16x16x32_bf16 v[74:77], v[242:245], v[210:213], v[74:77]
	v_mfma_f32_16x16x32_bf16 v[78:81], v[246:249], v[210:213], v[78:81]
	v_mfma_f32_16x16x32_bf16 v[82:85], v[234:237], v[214:217], v[82:85]
	v_mfma_f32_16x16x32_bf16 v[86:89], v[238:241], v[214:217], v[86:89]
	v_mfma_f32_16x16x32_bf16 v[90:93], v[242:245], v[214:217], v[90:93]
	v_mfma_f32_16x16x32_bf16 v[94:97], v[246:249], v[214:217], v[94:97]
	v_mfma_f32_16x16x32_bf16 v[98:101], v[234:237], v[218:221], v[98:101]
	v_mfma_f32_16x16x32_bf16 v[102:105], v[238:241], v[218:221], v[102:105]
	v_mfma_f32_16x16x32_bf16 v[106:109], v[242:245], v[218:221], v[106:109]
	v_mfma_f32_16x16x32_bf16 v[110:113], v[246:249], v[218:221], v[110:113]
	v_mfma_f32_16x16x32_bf16 v[114:117], v[234:237], v[222:225], v[114:117]
	v_mfma_f32_16x16x32_bf16 v[118:121], v[238:241], v[222:225], v[118:121]
	v_mfma_f32_16x16x32_bf16 v[122:125], v[242:245], v[222:225], v[122:125]
	v_mfma_f32_16x16x32_bf16 v[126:129], v[246:249], v[222:225], v[126:129]
	v_mfma_f32_16x16x32_bf16 v[130:133], v[234:237], v[226:229], v[130:133]
	v_mfma_f32_16x16x32_bf16 v[134:137], v[238:241], v[226:229], v[134:137]
	v_mfma_f32_16x16x32_bf16 v[138:141], v[242:245], v[226:229], v[138:141]
	v_mfma_f32_16x16x32_bf16 v[142:145], v[246:249], v[226:229], v[142:145]
	v_mfma_f32_16x16x32_bf16 v[146:149], v[234:237], v[230:233], v[146:149]
	v_mfma_f32_16x16x32_bf16 v[150:153], v[238:241], v[230:233], v[150:153]
	v_mfma_f32_16x16x32_bf16 v[154:157], v[242:245], v[230:233], v[154:157]
	v_mfma_f32_16x16x32_bf16 v[158:161], v[246:249], v[230:233], v[158:161]
	s_setprio 0
	v_lshl_add_u32 v167, v188, 1, s2
	v_add_u32_e32 v169, v167, v187
	ds_read_b128 v[192:195], v169
	ds_read_b128 v[206:209], v169 offset:2048
	ds_read_b128 v[210:213], v169 offset:4096
	ds_read_b128 v[214:217], v169 offset:6144
	ds_read_b128 v[218:221], v169 offset:8192
	ds_read_b128 v[222:225], v169 offset:10240
	ds_read_b128 v[226:229], v169 offset:12288
	ds_read_b128 v[230:233], v169 offset:14336
	v_add_u32_e32 v167, v167, v186
	ds_read_b128 v[234:237], v167 offset:32768
	ds_read_b128 v[238:241], v167 offset:34816
	ds_read_b128 v[242:245], v167 offset:36864
	ds_read_b128 v[246:249], v167 offset:38912
	s_cmp_lg_u32 s101, 0
	s_cbranch_scc1 .Lstg_134_b2
; DI f32x4 mfma16(bf16x8 a, bf16x8 b, f32x4 c) { return __builtin_amdgcn_mfma_f32_16x16x32_bf16(a, b, c, 0, 0, 0); }
; #pragma unroll
;   for (int ks = KS0; ks < KS1; ++ks) {
;     bf16x8 af[8], bfr[4];
; #pragma unroll
;     for (int i = 0; i < 8; ++i) {
;       const int r = wm * 128 + i * 16 + (lane & 15);
;       af[i] = *(const bf16x8*)(S + r * 64 + (((ks * 4 + (lane >> 4)) ^ ((r >> 1) & 7)) << 3));
;     }
; #pragma unroll
;     for (int j = 0; j < 4; ++j) {
;       const int r = wn * 64 + j * 16 + (lane & 15);
;       bfr[j] = *(const bf16x8*)(S + 16384 + r * 64 + (((ks * 4 + (lane >> 4)) ^ ((r >> 1) & 7)) << 3));
;     }
;     __builtin_amdgcn_s_setprio(1);
; #pragma unroll
;     for (int i = 0; i < 8; ++i)
; #pragma unroll
;       for (int j = 0; j < 4; ++j) acc[i][j] = mfma16(bfr[j], af[i], acc[i][j]);
;     __builtin_amdgcn_s_setprio(0);
;   }
; }
; DI void gemm8_accum(f32x4 (&acc)[8][4], const bf16_t* a, size_t lda, const bf16_t* b, size_t ldb, int nkb, bf16_t* L,
;                     const bool pre, const bf16_t* an, size_t ldan, const bf16_t* bn, size_t ldbn) {
;     ...
;   for (int kb = 0; kb + 2 < nkb; ++kb) {
;     __syncthreads();
;     g8_store1(L + ((kb + 1) & 1) * 32768, ra, lrow, lch);
;     g8_load1o(ra, a + (kb + 2) * 64, offa);
;     __builtin_amdgcn_sched_barrier(0);
;     g8_compute<0, 1>(acc, L + (kb & 1) * 32768, wm, wn, lane);
;     __builtin_amdgcn_sched_barrier(0);
;     g8_store1(L + ((kb + 1) & 1) * 32768 + 16384, rb, lrow, lch);
;     g8_load1o(rb, b + (kb + 2) * 64, offb);
;     __builtin_amdgcn_sched_barrier(0);
;     g8_compute<1, 2>(acc, L + (kb & 1) * 32768, wm, wn, lane);
;   }
	s_setprio 1
	s_waitcnt lgkmcnt(3)
	v_mfma_f32_16x16x32_bf16 v[34:37], v[234:237], v[192:195], v[34:37]
	s_waitcnt lgkmcnt(2)
	v_mfma_f32_16x16x32_bf16 v[38:41], v[238:241], v[192:195], v[38:41]
	s_waitcnt lgkmcnt(1)
	v_mfma_f32_16x16x32_bf16 v[42:45], v[242:245], v[192:195], v[42:45]
	s_waitcnt lgkmcnt(0)
	s_waitcnt vmcnt(7)
	ds_write_b128 v199, v[6:9] offset:32768
	s_waitcnt vmcnt(6)
	ds_write_b128 v199, v[2:5] offset:40960
	s_waitcnt vmcnt(5)
	ds_write_b128 v199, v[10:13] offset:49152
	s_waitcnt vmcnt(4)
	ds_write_b128 v199, v[14:17] offset:57344
	v_lshl_add_u64 v[2:3], v[176:177], 0, s[0:1]
	v_lshl_add_u64 v[4:5], v[174:175], 0, s[0:1]
	v_lshl_add_u64 v[10:11], v[172:173], 0, s[0:1]
	v_lshl_add_u64 v[14:15], v[170:171], 0, s[0:1]
	global_load_dwordx4 v[6:9], v[2:3], off
	s_nop 0
	global_load_dwordx4 v[2:5], v[4:5], off
	s_nop 0
	global_load_dwordx4 v[10:13], v[10:11], off
	s_nop 0
	global_load_dwordx4 v[14:17], v[14:15], off
	v_mfma_f32_16x16x32_bf16 v[46:49], v[246:249], v[192:195], v[46:49]
	v_mfma_f32_16x16x32_bf16 v[50:53], v[234:237], v[206:209], v[50:53]
	v_mfma_f32_16x16x32_bf16 v[54:57], v[238:241], v[206:209], v[54:57]
	v_mfma_f32_16x16x32_bf16 v[58:61], v[242:245], v[206:209], v[58:61]
	v_mfma_f32_16x16x32_bf16 v[62:65], v[246:249], v[206:209], v[62:65]
	v_mfma_f32_16x16x32_bf16 v[66:69], v[234:237], v[210:213], v[66:69]
	v_mfma_f32_16x16x32_bf16 v[70:73], v[238:241], v[210:213], v[70:73]
	v_mfma_f32_16x16x32_bf16 v[74:77], v[242:245], v[210:213], v[74:77]
	v_mfma_f32_16x16x32_bf16 v[78:81], v[246:249], v[210:213], v[78:81]
	v_mfma_f32_16x16x32_bf16 v[82:85], v[234:237], v[214:217], v[82:85]
	v_mfma_f32_16x16x32_bf16 v[86:89], v[238:241], v[214:217], v[86:89]
	v_mfma_f32_16x16x32_bf16 v[90:93], v[242:245], v[214:217], v[90:93]
	v_mfma_f32_16x16x32_bf16 v[94:97], v[246:249], v[214:217], v[94:97]
	v_mfma_f32_16x16x32_bf16 v[98:101], v[234:237], v[218:221], v[98:101]
	v_mfma_f32_16x16x32_bf16 v[102:105], v[238:241], v[218:221], v[102:105]
	v_mfma_f32_16x16x32_bf16 v[106:109], v[242:245], v[218:221], v[106:109]
	v_mfma_f32_16x16x32_bf16 v[110:113], v[246:249], v[218:221], v[110:113]
	v_mfma_f32_16x16x32_bf16 v[114:117], v[234:237], v[222:225], v[114:117]
	v_mfma_f32_16x16x32_bf16 v[118:121], v[238:241], v[222:225], v[118:121]
	v_mfma_f32_16x16x32_bf16 v[122:125], v[242:245], v[222:225], v[122:125]
	v_mfma_f32_16x16x32_bf16 v[126:129], v[246:249], v[222:225], v[126:129]
	v_mfma_f32_16x16x32_bf16 v[130:133], v[234:237], v[226:229], v[130:133]
	v_mfma_f32_16x16x32_bf16 v[134:137], v[238:241], v[226:229], v[134:137]
	v_mfma_f32_16x16x32_bf16 v[138:141], v[242:245], v[226:229], v[138:141]
	v_mfma_f32_16x16x32_bf16 v[142:145], v[246:249], v[226:229], v[142:145]
	v_mfma_f32_16x16x32_bf16 v[146:149], v[234:237], v[230:233], v[146:149]
	v_mfma_f32_16x16x32_bf16 v[150:153], v[238:241], v[230:233], v[150:153]
	v_mfma_f32_16x16x32_bf16 v[154:157], v[242:245], v[230:233], v[154:157]
	v_mfma_f32_16x16x32_bf16 v[158:161], v[246:249], v[230:233], v[158:161]
	s_setprio 0
	s_branch .Lstg_134_b
.Lstg_134_b2:
	s_waitcnt vmcnt(7)
	ds_write_b128 v199, v[6:9] offset:32768
	s_waitcnt vmcnt(6)
	ds_write_b128 v199, v[2:5] offset:40960
	s_waitcnt vmcnt(5)
	ds_write_b128 v199, v[10:13] offset:49152
	s_waitcnt vmcnt(4)
	ds_write_b128 v199, v[14:17] offset:57344
	v_lshl_add_u64 v[2:3], v[176:177], 0, s[0:1]
	v_lshl_add_u64 v[4:5], v[174:175], 0, s[0:1]
	v_lshl_add_u64 v[10:11], v[172:173], 0, s[0:1]
	v_lshl_add_u64 v[14:15], v[170:171], 0, s[0:1]
	global_load_dwordx4 v[6:9], v[2:3], off
	s_nop 0
	global_load_dwordx4 v[2:5], v[4:5], off
	s_nop 0
	global_load_dwordx4 v[10:13], v[10:11], off
	s_nop 0
	global_load_dwordx4 v[14:17], v[14:15], off

; DI f32x4 mfma16(bf16x8 a, bf16x8 b, f32x4 c) { return __builtin_amdgcn_mfma_f32_16x16x32_bf16(a, b, c, 0, 0, 0); }
; #pragma unroll
;   for (int ks = KS0; ks < KS1; ++ks) {
;     bf16x8 af[8], bfr[4];
; #pragma unroll
;     for (int i = 0; i < 8; ++i) {
;       const int r = wm * 128 + i * 16 + (lane & 15);
;       af[i] = *(const bf16x8*)(S + r * 64 + (((ks * 4 + (lane >> 4)) ^ ((r >> 1) & 7)) << 3));
;     }
; #pragma unroll
;     for (int j = 0; j < 4; ++j) {
;       const int r = wn * 64 + j * 16 + (lane & 15);
;       bfr[j] = *(const bf16x8*)(S + 16384 + r * 64 + (((ks * 4 + (lane >> 4)) ^ ((r >> 1) & 7)) << 3));
;     }
;     __builtin_amdgcn_s_setprio(1);
; #pragma unroll
;     for (int i = 0; i < 8; ++i)
; #pragma unroll
;       for (int j = 0; j < 4; ++j) acc[i][j] = mfma16(bfr[j], af[i], acc[i][j]);
;     __builtin_amdgcn_s_setprio(0);
;   }
; }
; DI void gemm8_accum(f32x4 (&acc)[8][4], const bf16_t* a, size_t lda, const bf16_t* b, size_t ldb, int nkb, bf16_t* L,
;                     const bool pre, const bf16_t* an, size_t ldan, const bf16_t* bn, size_t ldbn) {
;     ...
;   for (int kb = 0; kb + 2 < nkb; ++kb) {
;     __syncthreads();
;     g8_store1(L + ((kb + 1) & 1) * 32768, ra, lrow, lch);
;     g8_load1o(ra, a + (kb + 2) * 64, offa);
;     __builtin_amdgcn_sched_barrier(0);
;     g8_compute<0, 1>(acc, L + (kb & 1) * 32768, wm, wn, lane);
;     __builtin_amdgcn_sched_barrier(0);
;     g8_store1(L + ((kb + 1) & 1) * 32768 + 16384, rb, lrow, lch);
;     g8_load1o(rb, b + (kb + 2) * 64, offb);
;     __builtin_amdgcn_sched_barrier(0);
;     g8_compute<1, 2>(acc, L + (kb & 1) * 32768, wm, wn, lane);
;   }
.LBB0_778:
	s_add_i32 s3, s2, 0x8000
	s_and_b32 s20, s3, 0x8000
	v_lshl_add_u32 v191, s20, 1, v163
	v_lshl_add_u32 v204, s20, 1, v163
	s_waitcnt lgkmcnt(0)
	s_barrier
	s_cmp_eq_u32 s100, 0
	s_cbranch_scc1 .Lstg_778_a
	s_setprio 1
	v_mfma_f32_16x16x32_bf16 v[158:161], v[230:233], v[192:195], v[158:161]
	v_mfma_f32_16x16x32_bf16 v[154:157], v[234:237], v[192:195], v[154:157]
	v_mfma_f32_16x16x32_bf16 v[150:153], v[238:241], v[192:195], v[150:153]
	v_mfma_f32_16x16x32_bf16 v[146:149], v[242:245], v[192:195], v[146:149]
	v_mfma_f32_16x16x32_bf16 v[142:145], v[230:233], v[198:201], v[142:145]
	v_mfma_f32_16x16x32_bf16 v[138:141], v[234:237], v[198:201], v[138:141]
	v_mfma_f32_16x16x32_bf16 v[134:137], v[238:241], v[198:201], v[134:137]
	v_mfma_f32_16x16x32_bf16 v[130:133], v[242:245], v[198:201], v[130:133]
	v_mfma_f32_16x16x32_bf16 v[126:129], v[230:233], v[206:209], v[126:129]
	v_mfma_f32_16x16x32_bf16 v[122:125], v[234:237], v[206:209], v[122:125]
	v_mfma_f32_16x16x32_bf16 v[118:121], v[238:241], v[206:209], v[118:121]
	v_mfma_f32_16x16x32_bf16 v[114:117], v[242:245], v[206:209], v[114:117]
	v_mfma_f32_16x16x32_bf16 v[110:113], v[230:233], v[210:213], v[110:113]
	v_mfma_f32_16x16x32_bf16 v[106:109], v[234:237], v[210:213], v[106:109]
	v_mfma_f32_16x16x32_bf16 v[102:105], v[238:241], v[210:213], v[102:105]
	v_mfma_f32_16x16x32_bf16 v[98:101], v[242:245], v[210:213], v[98:101]
	v_mfma_f32_16x16x32_bf16 v[94:97], v[230:233], v[214:217], v[94:97]
	v_mfma_f32_16x16x32_bf16 v[90:93], v[234:237], v[214:217], v[90:93]
	v_mfma_f32_16x16x32_bf16 v[86:89], v[238:241], v[214:217], v[86:89]
	v_mfma_f32_16x16x32_bf16 v[82:85], v[242:245], v[214:217], v[82:85]
	v_mfma_f32_16x16x32_bf16 v[78:81], v[230:233], v[218:221], v[78:81]
	v_mfma_f32_16x16x32_bf16 v[74:77], v[234:237], v[218:221], v[74:77]
	v_mfma_f32_16x16x32_bf16 v[70:73], v[238:241], v[218:221], v[70:73]
	v_mfma_f32_16x16x32_bf16 v[66:69], v[242:245], v[218:221], v[66:69]
	v_mfma_f32_16x16x32_bf16 v[62:65], v[230:233], v[222:225], v[62:65]
	v_mfma_f32_16x16x32_bf16 v[58:61], v[234:237], v[222:225], v[58:61]
	v_mfma_f32_16x16x32_bf16 v[54:57], v[238:241], v[222:225], v[54:57]
	v_mfma_f32_16x16x32_bf16 v[50:53], v[242:245], v[222:225], v[50:53]
	v_mfma_f32_16x16x32_bf16 v[46:49], v[230:233], v[226:229], v[46:49]
	v_mfma_f32_16x16x32_bf16 v[42:45], v[234:237], v[226:229], v[42:45]
	v_mfma_f32_16x16x32_bf16 v[38:41], v[238:241], v[226:229], v[38:41]
	v_mfma_f32_16x16x32_bf16 v[34:37], v[242:245], v[226:229], v[34:37]
	s_setprio 0
.Lstg_778_a:
	s_and_b32 s2, s2, 0x8000
	s_lshl_b32 s2, s2, 1
	s_add_i32 s2, s2, 0
	v_lshl_add_u32 v202, v169, 1, s2
	v_add_u32_e32 v203, v202, v188
	ds_read_b128 v[192:195], v203
	ds_read_b128 v[198:201], v203 offset:2048
	ds_read_b128 v[206:209], v203 offset:4096
	ds_read_b128 v[210:213], v203 offset:6144
	ds_read_b128 v[214:217], v203 offset:8192
	ds_read_b128 v[218:221], v203 offset:10240
	ds_read_b128 v[222:225], v203 offset:12288
	ds_read_b128 v[226:229], v203 offset:14336
	v_add_u32_e32 v202, v202, v171
	ds_read_b128 v[230:233], v202 offset:32768
	ds_read_b128 v[234:237], v202 offset:34816
	ds_read_b128 v[238:241], v202 offset:36864
	ds_read_b128 v[242:245], v202 offset:38912
	s_setprio 1
	s_waitcnt lgkmcnt(3)
	v_mfma_f32_16x16x32_bf16 v[158:161], v[230:233], v[192:195], v[158:161]
	s_waitcnt lgkmcnt(2)
	v_mfma_f32_16x16x32_bf16 v[154:157], v[234:237], v[192:195], v[154:157]
	s_waitcnt lgkmcnt(1)
	v_mfma_f32_16x16x32_bf16 v[150:153], v[238:241], v[192:195], v[150:153]
	s_waitcnt lgkmcnt(0)
	s_waitcnt vmcnt(5)
	ds_write_b128 v191, v[22:25]
	ds_write_b128 v191, v[18:21] offset:8192
	ds_write_b128 v191, v[26:29] offset:16384
	s_waitcnt vmcnt(4)
	ds_write_b128 v191, v[30:33] offset:24576
	v_lshl_add_u64 v[18:19], v[186:187], 0, s[0:1]
	v_lshl_add_u64 v[26:27], v[182:183], 0, s[0:1]
	global_load_dwordx4 v[22:25], v[18:19], off
	v_lshl_add_u64 v[30:31], v[180:181], 0, s[0:1]
	global_load_dwordx4 v[26:29], v[26:27], off
	v_lshl_add_u64 v[18:19], v[184:185], 0, s[0:1]
	global_load_dwordx4 v[18:21], v[18:19], off
	s_nop 0
	global_load_dwordx4 v[30:33], v[30:31], off
	v_mfma_f32_16x16x32_bf16 v[146:149], v[242:245], v[192:195], v[146:149]
	v_mfma_f32_16x16x32_bf16 v[142:145], v[230:233], v[198:201], v[142:145]
	v_mfma_f32_16x16x32_bf16 v[138:141], v[234:237], v[198:201], v[138:141]
	v_mfma_f32_16x16x32_bf16 v[134:137], v[238:241], v[198:201], v[134:137]
	v_mfma_f32_16x16x32_bf16 v[130:133], v[242:245], v[198:201], v[130:133]
	v_mfma_f32_16x16x32_bf16 v[126:129], v[230:233], v[206:209], v[126:129]
	v_mfma_f32_16x16x32_bf16 v[122:125], v[234:237], v[206:209], v[122:125]
	v_mfma_f32_16x16x32_bf16 v[118:121], v[238:241], v[206:209], v[118:121]
	v_mfma_f32_16x16x32_bf16 v[114:117], v[242:245], v[206:209], v[114:117]
	v_mfma_f32_16x16x32_bf16 v[110:113], v[230:233], v[210:213], v[110:113]
	v_mfma_f32_16x16x32_bf16 v[106:109], v[234:237], v[210:213], v[106:109]
	v_mfma_f32_16x16x32_bf16 v[102:105], v[238:241], v[210:213], v[102:105]
	v_mfma_f32_16x16x32_bf16 v[98:101], v[242:245], v[210:213], v[98:101]
	v_mfma_f32_16x16x32_bf16 v[94:97], v[230:233], v[214:217], v[94:97]
	v_mfma_f32_16x16x32_bf16 v[90:93], v[234:237], v[214:217], v[90:93]
	v_mfma_f32_16x16x32_bf16 v[86:89], v[238:241], v[214:217], v[86:89]
	v_mfma_f32_16x16x32_bf16 v[82:85], v[242:245], v[214:217], v[82:85]
	v_mfma_f32_16x16x32_bf16 v[78:81], v[230:233], v[218:221], v[78:81]
	v_mfma_f32_16x16x32_bf16 v[74:77], v[234:237], v[218:221], v[74:77]
	v_mfma_f32_16x16x32_bf16 v[70:73], v[238:241], v[218:221], v[70:73]
	v_mfma_f32_16x16x32_bf16 v[66:69], v[242:245], v[218:221], v[66:69]
	v_mfma_f32_16x16x32_bf16 v[62:65], v[230:233], v[222:225], v[62:65]
	v_mfma_f32_16x16x32_bf16 v[58:61], v[234:237], v[222:225], v[58:61]
	v_mfma_f32_16x16x32_bf16 v[54:57], v[238:241], v[222:225], v[54:57]
	v_mfma_f32_16x16x32_bf16 v[50:53], v[242:245], v[222:225], v[50:53]
	v_mfma_f32_16x16x32_bf16 v[46:49], v[230:233], v[226:229], v[46:49]
	v_mfma_f32_16x16x32_bf16 v[42:45], v[234:237], v[226:229], v[42:45]
	v_mfma_f32_16x16x32_bf16 v[38:41], v[238:241], v[226:229], v[38:41]
	v_mfma_f32_16x16x32_bf16 v[34:37], v[242:245], v[226:229], v[34:37]
	s_setprio 0
	v_lshl_add_u32 v191, v189, 1, s2
	v_add_u32_e32 v202, v191, v188
	ds_read_b128 v[192:195], v202
	ds_read_b128 v[198:201], v202 offset:2048
	ds_read_b128 v[206:209], v202 offset:4096
	ds_read_b128 v[210:213], v202 offset:6144
	ds_read_b128 v[214:217], v202 offset:8192
	ds_read_b128 v[218:221], v202 offset:10240
	ds_read_b128 v[222:225], v202 offset:12288
	ds_read_b128 v[226:229], v202 offset:14336
	v_add_u32_e32 v191, v191, v171
	ds_read_b128 v[230:233], v191 offset:32768
	ds_read_b128 v[234:237], v191 offset:34816
	ds_read_b128 v[238:241], v191 offset:36864
	ds_read_b128 v[242:245], v191 offset:38912
	s_cmp_lg_u32 s101, 0
	s_cbranch_scc1 .Lstg_778_b2
; DI f32x4 mfma16(bf16x8 a, bf16x8 b, f32x4 c) { return __builtin_amdgcn_mfma_f32_16x16x32_bf16(a, b, c, 0, 0, 0); }
; #pragma unroll
;   for (int ks = KS0; ks < KS1; ++ks) {
;     bf16x8 af[8], bfr[4];
; #pragma unroll
;     for (int i = 0; i < 8; ++i) {
;       const int r = wm * 128 + i * 16 + (lane & 15);
;       af[i] = *(const bf16x8*)(S + r * 64 + (((ks * 4 + (lane >> 4)) ^ ((r >> 1) & 7)) << 3));
;     }
; #pragma unroll
;     for (int j = 0; j < 4; ++j) {
;       const int r = wn * 64 + j * 16 + (lane & 15);
;       bfr[j] = *(const bf16x8*)(S + 16384 + r * 64 + (((ks * 4 + (lane >> 4)) ^ ((r >> 1) & 7)) << 3));
;     }
;     __builtin_amdgcn_s_setprio(1);
; #pragma unroll
;     for (int i = 0; i < 8; ++i)
; #pragma unroll
;       for (int j = 0; j < 4; ++j) acc[i][j] = mfma16(bfr[j], af[i], acc[i][j]);
;     __builtin_amdgcn_s_setprio(0);
;   }
; }
; DI void gemm8_accum(f32x4 (&acc)[8][4], const bf16_t* a, size_t lda, const bf16_t* b, size_t ldb, int nkb, bf16_t* L,
;                     const bool pre, const bf16_t* an, size_t ldan, const bf16_t* bn, size_t ldbn) {
;     ...
;   for (int kb = 0; kb + 2 < nkb; ++kb) {
;     __syncthreads();
;     g8_store1(L + ((kb + 1) & 1) * 32768, ra, lrow, lch);
;     g8_load1o(ra, a + (kb + 2) * 64, offa);
;     __builtin_amdgcn_sched_barrier(0);
;     g8_compute<0, 1>(acc, L + (kb & 1) * 32768, wm, wn, lane);
;     __builtin_amdgcn_sched_barrier(0);
;     g8_store1(L + ((kb + 1) & 1) * 32768 + 16384, rb, lrow, lch);
;     g8_load1o(rb, b + (kb + 2) * 64, offb);
;     __builtin_amdgcn_sched_barrier(0);
;     g8_compute<1, 2>(acc, L + (kb & 1) * 32768, wm, wn, lane);
;   }
	s_setprio 1
	s_waitcnt lgkmcnt(3)
	v_mfma_f32_16x16x32_bf16 v[158:161], v[230:233], v[192:195], v[158:161]
	s_waitcnt lgkmcnt(2)
	v_mfma_f32_16x16x32_bf16 v[154:157], v[234:237], v[192:195], v[154:157]
	s_waitcnt lgkmcnt(1)
	v_mfma_f32_16x16x32_bf16 v[150:153], v[238:241], v[192:195], v[150:153]
	s_waitcnt lgkmcnt(0)
	s_waitcnt vmcnt(7)
	ds_write_b128 v204, v[14:17] offset:32768
	s_waitcnt vmcnt(6)
	ds_write_b128 v204, v[2:5] offset:40960
	s_waitcnt vmcnt(5)
	ds_write_b128 v204, v[6:9] offset:49152
	s_waitcnt vmcnt(4)
	ds_write_b128 v204, v[10:13] offset:57344
	v_lshl_add_u64 v[2:3], v[178:179], 0, s[0:1]
	v_lshl_add_u64 v[4:5], v[176:177], 0, s[0:1]
	v_lshl_add_u64 v[6:7], v[174:175], 0, s[0:1]
	v_lshl_add_u64 v[10:11], v[172:173], 0, s[0:1]
	global_load_dwordx4 v[14:17], v[2:3], off
	s_nop 0
	global_load_dwordx4 v[2:5], v[4:5], off
	s_nop 0
	global_load_dwordx4 v[6:9], v[6:7], off
	s_nop 0
	global_load_dwordx4 v[10:13], v[10:11], off
	v_mfma_f32_16x16x32_bf16 v[146:149], v[242:245], v[192:195], v[146:149]
	v_mfma_f32_16x16x32_bf16 v[142:145], v[230:233], v[198:201], v[142:145]
	v_mfma_f32_16x16x32_bf16 v[138:141], v[234:237], v[198:201], v[138:141]
	v_mfma_f32_16x16x32_bf16 v[134:137], v[238:241], v[198:201], v[134:137]
	v_mfma_f32_16x16x32_bf16 v[130:133], v[242:245], v[198:201], v[130:133]
	v_mfma_f32_16x16x32_bf16 v[126:129], v[230:233], v[206:209], v[126:129]
	v_mfma_f32_16x16x32_bf16 v[122:125], v[234:237], v[206:209], v[122:125]
	v_mfma_f32_16x16x32_bf16 v[118:121], v[238:241], v[206:209], v[118:121]
	v_mfma_f32_16x16x32_bf16 v[114:117], v[242:245], v[206:209], v[114:117]
	v_mfma_f32_16x16x32_bf16 v[110:113], v[230:233], v[210:213], v[110:113]
	v_mfma_f32_16x16x32_bf16 v[106:109], v[234:237], v[210:213], v[106:109]
	v_mfma_f32_16x16x32_bf16 v[102:105], v[238:241], v[210:213], v[102:105]
	v_mfma_f32_16x16x32_bf16 v[98:101], v[242:245], v[210:213], v[98:101]
	v_mfma_f32_16x16x32_bf16 v[94:97], v[230:233], v[214:217], v[94:97]
	v_mfma_f32_16x16x32_bf16 v[90:93], v[234:237], v[214:217], v[90:93]
	v_mfma_f32_16x16x32_bf16 v[86:89], v[238:241], v[214:217], v[86:89]
	v_mfma_f32_16x16x32_bf16 v[82:85], v[242:245], v[214:217], v[82:85]
	v_mfma_f32_16x16x32_bf16 v[78:81], v[230:233], v[218:221], v[78:81]
	v_mfma_f32_16x16x32_bf16 v[74:77], v[234:237], v[218:221], v[74:77]
	v_mfma_f32_16x16x32_bf16 v[70:73], v[238:241], v[218:221], v[70:73]
	v_mfma_f32_16x16x32_bf16 v[66:69], v[242:245], v[218:221], v[66:69]
	v_mfma_f32_16x16x32_bf16 v[62:65], v[230:233], v[222:225], v[62:65]
	v_mfma_f32_16x16x32_bf16 v[58:61], v[234:237], v[222:225], v[58:61]
	v_mfma_f32_16x16x32_bf16 v[54:57], v[238:241], v[222:225], v[54:57]
	v_mfma_f32_16x16x32_bf16 v[50:53], v[242:245], v[222:225], v[50:53]
	v_mfma_f32_16x16x32_bf16 v[46:49], v[230:233], v[226:229], v[46:49]
	v_mfma_f32_16x16x32_bf16 v[42:45], v[234:237], v[226:229], v[42:45]
	v_mfma_f32_16x16x32_bf16 v[38:41], v[238:241], v[226:229], v[38:41]
	v_mfma_f32_16x16x32_bf16 v[34:37], v[242:245], v[226:229], v[34:37]
	s_setprio 0
	s_branch .Lstg_778_b
.Lstg_778_b2:
	s_waitcnt vmcnt(7)
	ds_write_b128 v204, v[14:17] offset:32768
	s_waitcnt vmcnt(6)
	ds_write_b128 v204, v[2:5] offset:40960
	s_waitcnt vmcnt(5)
	ds_write_b128 v204, v[6:9] offset:49152
	s_waitcnt vmcnt(4)
	ds_write_b128 v204, v[10:13] offset:57344
	v_lshl_add_u64 v[2:3], v[178:179], 0, s[0:1]
	v_lshl_add_u64 v[4:5], v[176:177], 0, s[0:1]
	v_lshl_add_u64 v[6:7], v[174:175], 0, s[0:1]
	v_lshl_add_u64 v[10:11], v[172:173], 0, s[0:1]
	global_load_dwordx4 v[14:17], v[2:3], off
	s_nop 0
	global_load_dwordx4 v[2:5], v[4:5], off
	s_nop 0
	global_load_dwordx4 v[6:9], v[6:7], off
	s_nop 0
	global_load_dwordx4 v[10:13], v[10:11], off

; DI f32x4 mfma16(bf16x8 a, bf16x8 b, f32x4 c) { return __builtin_amdgcn_mfma_f32_16x16x32_bf16(a, b, c, 0, 0, 0); }
; #pragma unroll
;   for (int ks = KS0; ks < KS1; ++ks) {
;     bf16x8 af[8], bfr[4];
; #pragma unroll
;     for (int i = 0; i < 8; ++i) {
;       const int r = wm * 128 + i * 16 + (lane & 15);
;       af[i] = *(const bf16x8*)(S + r * 64 + (((ks * 4 + (lane >> 4)) ^ ((r >> 1) & 7)) << 3));
;     }
; #pragma unroll
;     for (int j = 0; j < 4; ++j) {
;       const int r = wn * 64 + j * 16 + (lane & 15);
;       bfr[j] = *(const bf16x8*)(S + 16384 + r * 64 + (((ks * 4 + (lane >> 4)) ^ ((r >> 1) & 7)) << 3));
;     }
;     __builtin_amdgcn_s_setprio(1);
; #pragma unroll
;     for (int i = 0; i < 8; ++i)
; #pragma unroll
;       for (int j = 0; j < 4; ++j) acc[i][j] = mfma16(bfr[j], af[i], acc[i][j]);
;     __builtin_amdgcn_s_setprio(0);
;   }
; }
; DI void gemm8_accum(f32x4 (&acc)[8][4], const bf16_t* a, size_t lda, const bf16_t* b, size_t ldb, int nkb, bf16_t* L,
;                     const bool pre, const bf16_t* an, size_t ldan, const bf16_t* bn, size_t ldbn) {
;     ...
;   for (int kb = 0; kb + 2 < nkb; ++kb) {
;     __syncthreads();
;     g8_store1(L + ((kb + 1) & 1) * 32768, ra, lrow, lch);
;     g8_load1o(ra, a + (kb + 2) * 64, offa);
;     __builtin_amdgcn_sched_barrier(0);
;     g8_compute<0, 1>(acc, L + (kb & 1) * 32768, wm, wn, lane);
;     __builtin_amdgcn_sched_barrier(0);
;     g8_store1(L + ((kb + 1) & 1) * 32768 + 16384, rb, lrow, lch);
;     g8_load1o(rb, b + (kb + 2) * 64, offb);
;     __builtin_amdgcn_sched_barrier(0);
;     g8_compute<1, 2>(acc, L + (kb & 1) * 32768, wm, wn, lane);
;   }
.LBB0_780:
	s_add_i32 s3, s2, 0x8000
	s_and_b32 s6, s3, 0x8000
	v_lshl_add_u32 v193, s6, 1, v0
	v_lshl_add_u32 v204, s6, 1, v0
	s_waitcnt lgkmcnt(0)
	s_barrier
	s_cmp_eq_u32 s100, 0
	s_cbranch_scc1 .Lstg_780_a
	s_setprio 1
	v_mfma_f32_16x16x32_bf16 v[2:5], v[234:237], v[198:201], v[2:5]
	v_mfma_f32_16x16x32_bf16 v[6:9], v[238:241], v[198:201], v[6:9]
	v_mfma_f32_16x16x32_bf16 v[10:13], v[242:245], v[198:201], v[10:13]
	v_mfma_f32_16x16x32_bf16 v[14:17], v[246:249], v[198:201], v[14:17]
	v_mfma_f32_16x16x32_bf16 v[22:25], v[234:237], v[206:209], v[22:25]
	v_mfma_f32_16x16x32_bf16 v[30:33], v[238:241], v[206:209], v[30:33]
	v_mfma_f32_16x16x32_bf16 v[38:41], v[242:245], v[206:209], v[38:41]
	v_mfma_f32_16x16x32_bf16 v[46:49], v[246:249], v[206:209], v[46:49]
	v_mfma_f32_16x16x32_bf16 v[54:57], v[234:237], v[210:213], v[54:57]
	v_mfma_f32_16x16x32_bf16 v[62:65], v[238:241], v[210:213], v[62:65]
	v_mfma_f32_16x16x32_bf16 v[70:73], v[242:245], v[210:213], v[70:73]
	v_mfma_f32_16x16x32_bf16 v[78:81], v[246:249], v[210:213], v[78:81]
	v_mfma_f32_16x16x32_bf16 v[86:89], v[234:237], v[214:217], v[86:89]
	v_mfma_f32_16x16x32_bf16 v[94:97], v[238:241], v[214:217], v[94:97]
	v_mfma_f32_16x16x32_bf16 v[102:105], v[242:245], v[214:217], v[102:105]
	v_mfma_f32_16x16x32_bf16 v[110:113], v[246:249], v[214:217], v[110:113]
	v_mfma_f32_16x16x32_bf16 v[118:121], v[234:237], v[218:221], v[118:121]
	v_mfma_f32_16x16x32_bf16 v[126:129], v[238:241], v[218:221], v[126:129]
	v_mfma_f32_16x16x32_bf16 v[122:125], v[242:245], v[218:221], v[122:125]
	v_mfma_f32_16x16x32_bf16 v[114:117], v[246:249], v[218:221], v[114:117]
	v_mfma_f32_16x16x32_bf16 v[106:109], v[234:237], v[222:225], v[106:109]
	v_mfma_f32_16x16x32_bf16 v[98:101], v[238:241], v[222:225], v[98:101]
	v_mfma_f32_16x16x32_bf16 v[90:93], v[242:245], v[222:225], v[90:93]
	v_mfma_f32_16x16x32_bf16 v[82:85], v[246:249], v[222:225], v[82:85]
	v_mfma_f32_16x16x32_bf16 v[74:77], v[234:237], v[226:229], v[74:77]
	v_mfma_f32_16x16x32_bf16 v[66:69], v[238:241], v[226:229], v[66:69]
	v_mfma_f32_16x16x32_bf16 v[58:61], v[242:245], v[226:229], v[58:61]
	v_mfma_f32_16x16x32_bf16 v[50:53], v[246:249], v[226:229], v[50:53]
	v_mfma_f32_16x16x32_bf16 v[42:45], v[234:237], v[230:233], v[42:45]
	v_mfma_f32_16x16x32_bf16 v[34:37], v[238:241], v[230:233], v[34:37]
	v_mfma_f32_16x16x32_bf16 v[26:29], v[242:245], v[230:233], v[26:29]
	v_mfma_f32_16x16x32_bf16 v[18:21], v[246:249], v[230:233], v[18:21]
	s_setprio 0
.Lstg_780_a:
	s_and_b32 s2, s2, 0x8000
	s_lshl_b32 s2, s2, 1
	s_add_i32 s2, s2, 0
	v_lshl_add_u32 v194, v192, 1, s2
	v_add_u32_e32 v195, v194, v189
	ds_read_b128 v[198:201], v195
	ds_read_b128 v[206:209], v195 offset:2048
	ds_read_b128 v[210:213], v195 offset:4096
	ds_read_b128 v[214:217], v195 offset:6144
	ds_read_b128 v[218:221], v195 offset:8192
	ds_read_b128 v[222:225], v195 offset:10240
	ds_read_b128 v[226:229], v195 offset:12288
	ds_read_b128 v[230:233], v195 offset:14336
	v_add_u32_e32 v194, v194, v188
	ds_read_b128 v[234:237], v194 offset:32768
	ds_read_b128 v[238:241], v194 offset:34816
	ds_read_b128 v[242:245], v194 offset:36864
	ds_read_b128 v[246:249], v194 offset:38912
	s_setprio 1
	s_waitcnt lgkmcnt(3)
	v_mfma_f32_16x16x32_bf16 v[2:5], v[234:237], v[198:201], v[2:5]
	s_waitcnt lgkmcnt(2)
	v_mfma_f32_16x16x32_bf16 v[6:9], v[238:241], v[198:201], v[6:9]
	s_waitcnt lgkmcnt(1)
	v_mfma_f32_16x16x32_bf16 v[10:13], v[242:245], v[198:201], v[10:13]
	s_waitcnt lgkmcnt(0)
	s_waitcnt vmcnt(7)
	ds_write_b128 v193, v[146:149]
	s_waitcnt vmcnt(5)
	ds_write_b128 v193, v[150:153] offset:8192
	s_waitcnt vmcnt(4)
	ds_write_b128 v193, v[154:157] offset:16384
	s_waitcnt vmcnt(3)
	ds_write_b128 v193, v[158:161] offset:24576
	v_lshl_add_u64 v[146:147], v[186:187], 0, s[0:1]
	v_lshl_add_u64 v[150:151], v[184:185], 0, s[0:1]
	v_lshl_add_u64 v[154:155], v[182:183], 0, s[0:1]
	v_lshl_add_u64 v[158:159], v[180:181], 0, s[0:1]
	global_load_dwordx4 v[146:149], v[146:147], off
	s_nop 0
	global_load_dwordx4 v[150:153], v[150:151], off
	s_nop 0
	global_load_dwordx4 v[154:157], v[154:155], off
	s_nop 0
	global_load_dwordx4 v[158:161], v[158:159], off
	v_mfma_f32_16x16x32_bf16 v[14:17], v[246:249], v[198:201], v[14:17]
	v_mfma_f32_16x16x32_bf16 v[22:25], v[234:237], v[206:209], v[22:25]
	v_mfma_f32_16x16x32_bf16 v[30:33], v[238:241], v[206:209], v[30:33]
	v_mfma_f32_16x16x32_bf16 v[38:41], v[242:245], v[206:209], v[38:41]
	v_mfma_f32_16x16x32_bf16 v[46:49], v[246:249], v[206:209], v[46:49]
	v_mfma_f32_16x16x32_bf16 v[54:57], v[234:237], v[210:213], v[54:57]
	v_mfma_f32_16x16x32_bf16 v[62:65], v[238:241], v[210:213], v[62:65]
	v_mfma_f32_16x16x32_bf16 v[70:73], v[242:245], v[210:213], v[70:73]
	v_mfma_f32_16x16x32_bf16 v[78:81], v[246:249], v[210:213], v[78:81]
	v_mfma_f32_16x16x32_bf16 v[86:89], v[234:237], v[214:217], v[86:89]
	v_mfma_f32_16x16x32_bf16 v[94:97], v[238:241], v[214:217], v[94:97]
	v_mfma_f32_16x16x32_bf16 v[102:105], v[242:245], v[214:217], v[102:105]
	v_mfma_f32_16x16x32_bf16 v[110:113], v[246:249], v[214:217], v[110:113]
	v_mfma_f32_16x16x32_bf16 v[118:121], v[234:237], v[218:221], v[118:121]
	v_mfma_f32_16x16x32_bf16 v[126:129], v[238:241], v[218:221], v[126:129]
	v_mfma_f32_16x16x32_bf16 v[122:125], v[242:245], v[218:221], v[122:125]
	v_mfma_f32_16x16x32_bf16 v[114:117], v[246:249], v[218:221], v[114:117]
	v_mfma_f32_16x16x32_bf16 v[106:109], v[234:237], v[222:225], v[106:109]
	v_mfma_f32_16x16x32_bf16 v[98:101], v[238:241], v[222:225], v[98:101]
	v_mfma_f32_16x16x32_bf16 v[90:93], v[242:245], v[222:225], v[90:93]
	v_mfma_f32_16x16x32_bf16 v[82:85], v[246:249], v[222:225], v[82:85]
	v_mfma_f32_16x16x32_bf16 v[74:77], v[234:237], v[226:229], v[74:77]
	v_mfma_f32_16x16x32_bf16 v[66:69], v[238:241], v[226:229], v[66:69]
	v_mfma_f32_16x16x32_bf16 v[58:61], v[242:245], v[226:229], v[58:61]
	v_mfma_f32_16x16x32_bf16 v[50:53], v[246:249], v[226:229], v[50:53]
	v_mfma_f32_16x16x32_bf16 v[42:45], v[234:237], v[230:233], v[42:45]
	v_mfma_f32_16x16x32_bf16 v[34:37], v[238:241], v[230:233], v[34:37]
	v_mfma_f32_16x16x32_bf16 v[26:29], v[242:245], v[230:233], v[26:29]
	v_mfma_f32_16x16x32_bf16 v[18:21], v[246:249], v[230:233], v[18:21]
	s_setprio 0
	v_lshl_add_u32 v193, v190, 1, s2
	v_add_u32_e32 v194, v193, v189
	ds_read_b128 v[198:201], v194
	ds_read_b128 v[206:209], v194 offset:2048
	ds_read_b128 v[210:213], v194 offset:4096
	ds_read_b128 v[214:217], v194 offset:6144
	ds_read_b128 v[218:221], v194 offset:8192
	ds_read_b128 v[222:225], v194 offset:10240
	ds_read_b128 v[226:229], v194 offset:12288
	ds_read_b128 v[230:233], v194 offset:14336
	v_add_u32_e32 v193, v193, v188
	ds_read_b128 v[234:237], v193 offset:32768
	ds_read_b128 v[238:241], v193 offset:34816
	ds_read_b128 v[242:245], v193 offset:36864
	ds_read_b128 v[246:249], v193 offset:38912
	s_cmp_lg_u32 s101, 0
	s_cbranch_scc1 .Lstg_780_b2
; DI f32x4 mfma16(bf16x8 a, bf16x8 b, f32x4 c) { return __builtin_amdgcn_mfma_f32_16x16x32_bf16(a, b, c, 0, 0, 0); }
; #pragma unroll
;   for (int ks = KS0; ks < KS1; ++ks) {
;     bf16x8 af[8], bfr[4];
; #pragma unroll
;     for (int i = 0; i < 8; ++i) {
;       const int r = wm * 128 + i * 16 + (lane & 15);
;       af[i] = *(const bf16x8*)(S + r * 64 + (((ks * 4 + (lane >> 4)) ^ ((r >> 1) & 7)) << 3));
;     }
; #pragma unroll
;     for (int j = 0; j < 4; ++j) {
;       const int r = wn * 64 + j * 16 + (lane & 15);
;       bfr[j] = *(const bf16x8*)(S + 16384 + r * 64 + (((ks * 4 + (lane >> 4)) ^ ((r >> 1) & 7)) << 3));
;     }
;     __builtin_amdgcn_s_setprio(1);
; #pragma unroll
;     for (int i = 0; i < 8; ++i)
; #pragma unroll
;       for (int j = 0; j < 4; ++j) acc[i][j] = mfma16(bfr[j], af[i], acc[i][j]);
;     __builtin_amdgcn_s_setprio(0);
;   }
; }
; DI void gemm8_accum(f32x4 (&acc)[8][4], const bf16_t* a, size_t lda, const bf16_t* b, size_t ldb, int nkb, bf16_t* L,
;                     const bool pre, const bf16_t* an, size_t ldan, const bf16_t* bn, size_t ldbn) {
;     ...
;   for (int kb = 0; kb + 2 < nkb; ++kb) {
;     __syncthreads();
;     g8_store1(L + ((kb + 1) & 1) * 32768, ra, lrow, lch);
;     g8_load1o(ra, a + (kb + 2) * 64, offa);
;     __builtin_amdgcn_sched_barrier(0);
;     g8_compute<0, 1>(acc, L + (kb & 1) * 32768, wm, wn, lane);
;     __builtin_amdgcn_sched_barrier(0);
;     g8_store1(L + ((kb + 1) & 1) * 32768 + 16384, rb, lrow, lch);
;     g8_load1o(rb, b + (kb + 2) * 64, offb);
;     __builtin_amdgcn_sched_barrier(0);
;     g8_compute<1, 2>(acc, L + (kb & 1) * 32768, wm, wn, lane);
;   }
	s_setprio 1
	s_waitcnt lgkmcnt(3)
	v_mfma_f32_16x16x32_bf16 v[2:5], v[234:237], v[198:201], v[2:5]
	s_waitcnt lgkmcnt(2)
	v_mfma_f32_16x16x32_bf16 v[6:9], v[238:241], v[198:201], v[6:9]
	s_waitcnt lgkmcnt(1)
	v_mfma_f32_16x16x32_bf16 v[10:13], v[242:245], v[198:201], v[10:13]
	s_waitcnt lgkmcnt(0)
	s_waitcnt vmcnt(6)
	ds_write_b128 v204, v[130:133] offset:32768
	s_waitcnt vmcnt(5)
	ds_write_b128 v204, v[138:141] offset:40960
	s_waitcnt vmcnt(4)
	ds_write_b128 v204, v[134:137] offset:49152
	ds_write_b128 v204, v[142:145] offset:57344
	v_lshl_add_u64 v[130:131], v[178:179], 0, s[0:1]
	v_lshl_add_u64 v[134:135], v[176:177], 0, s[0:1]
	global_load_dwordx4 v[130:133], v[130:131], off
	s_nop 0
	global_load_dwordx4 v[138:141], v[134:135], off
	v_lshl_add_u64 v[134:135], v[174:175], 0, s[0:1]
	v_lshl_add_u64 v[142:143], v[172:173], 0, s[0:1]
	global_load_dwordx4 v[134:137], v[134:135], off
	s_nop 0
	global_load_dwordx4 v[142:145], v[142:143], off
	v_mfma_f32_16x16x32_bf16 v[14:17], v[246:249], v[198:201], v[14:17]
	v_mfma_f32_16x16x32_bf16 v[22:25], v[234:237], v[206:209], v[22:25]
	v_mfma_f32_16x16x32_bf16 v[30:33], v[238:241], v[206:209], v[30:33]
	v_mfma_f32_16x16x32_bf16 v[38:41], v[242:245], v[206:209], v[38:41]
	v_mfma_f32_16x16x32_bf16 v[46:49], v[246:249], v[206:209], v[46:49]
	v_mfma_f32_16x16x32_bf16 v[54:57], v[234:237], v[210:213], v[54:57]
	v_mfma_f32_16x16x32_bf16 v[62:65], v[238:241], v[210:213], v[62:65]
	v_mfma_f32_16x16x32_bf16 v[70:73], v[242:245], v[210:213], v[70:73]
	v_mfma_f32_16x16x32_bf16 v[78:81], v[246:249], v[210:213], v[78:81]
	v_mfma_f32_16x16x32_bf16 v[86:89], v[234:237], v[214:217], v[86:89]
	v_mfma_f32_16x16x32_bf16 v[94:97], v[238:241], v[214:217], v[94:97]
	v_mfma_f32_16x16x32_bf16 v[102:105], v[242:245], v[214:217], v[102:105]
	v_mfma_f32_16x16x32_bf16 v[110:113], v[246:249], v[214:217], v[110:113]
	v_mfma_f32_16x16x32_bf16 v[118:121], v[234:237], v[218:221], v[118:121]
	v_mfma_f32_16x16x32_bf16 v[126:129], v[238:241], v[218:221], v[126:129]
	v_mfma_f32_16x16x32_bf16 v[122:125], v[242:245], v[218:221], v[122:125]
	v_mfma_f32_16x16x32_bf16 v[114:117], v[246:249], v[218:221], v[114:117]
	v_mfma_f32_16x16x32_bf16 v[106:109], v[234:237], v[222:225], v[106:109]
	v_mfma_f32_16x16x32_bf16 v[98:101], v[238:241], v[222:225], v[98:101]
	v_mfma_f32_16x16x32_bf16 v[90:93], v[242:245], v[222:225], v[90:93]
	v_mfma_f32_16x16x32_bf16 v[82:85], v[246:249], v[222:225], v[82:85]
	v_mfma_f32_16x16x32_bf16 v[74:77], v[234:237], v[226:229], v[74:77]
	v_mfma_f32_16x16x32_bf16 v[66:69], v[238:241], v[226:229], v[66:69]
	v_mfma_f32_16x16x32_bf16 v[58:61], v[242:245], v[226:229], v[58:61]
	v_mfma_f32_16x16x32_bf16 v[50:53], v[246:249], v[226:229], v[50:53]
	v_mfma_f32_16x16x32_bf16 v[42:45], v[234:237], v[230:233], v[42:45]
	v_mfma_f32_16x16x32_bf16 v[34:37], v[238:241], v[230:233], v[34:37]
	v_mfma_f32_16x16x32_bf16 v[26:29], v[242:245], v[230:233], v[26:29]
	v_mfma_f32_16x16x32_bf16 v[18:21], v[246:249], v[230:233], v[18:21]
	s_setprio 0
	s_branch .Lstg_780_b
.Lstg_780_b2:
	s_waitcnt vmcnt(6)
	ds_write_b128 v204, v[130:133] offset:32768
	s_waitcnt vmcnt(5)
	ds_write_b128 v204, v[138:141] offset:40960
	s_waitcnt vmcnt(4)
	ds_write_b128 v204, v[134:137] offset:49152
	ds_write_b128 v204, v[142:145] offset:57344
	v_lshl_add_u64 v[130:131], v[178:179], 0, s[0:1]
	v_lshl_add_u64 v[134:135], v[176:177], 0, s[0:1]
	global_load_dwordx4 v[130:133], v[130:131], off
	s_nop 0
	global_load_dwordx4 v[138:141], v[134:135], off
	v_lshl_add_u64 v[134:135], v[174:175], 0, s[0:1]
	v_lshl_add_u64 v[142:143], v[172:173], 0, s[0:1]
	global_load_dwordx4 v[134:137], v[134:135], off
	s_nop 0
	global_load_dwordx4 v[142:145], v[142:143], off

; DI f32x4 mfma16(bf16x8 a, bf16x8 b, f32x4 c) { return __builtin_amdgcn_mfma_f32_16x16x32_bf16(a, b, c, 0, 0, 0); }
; #pragma unroll
;   for (int ks = KS0; ks < KS1; ++ks) {
;     bf16x8 af[8], bfr[4];
; #pragma unroll
;     for (int i = 0; i < 8; ++i) {
;       const int r = wm * 128 + i * 16 + (lane & 15);
;       af[i] = *(const bf16x8*)(S + r * 64 + (((ks * 4 + (lane >> 4)) ^ ((r >> 1) & 7)) << 3));
;     }
; #pragma unroll
;     for (int j = 0; j < 4; ++j) {
;       const int r = wn * 64 + j * 16 + (lane & 15);
;       bfr[j] = *(const bf16x8*)(S + 16384 + r * 64 + (((ks * 4 + (lane >> 4)) ^ ((r >> 1) & 7)) << 3));
;     }
;     __builtin_amdgcn_s_setprio(1);
; #pragma unroll
;     for (int i = 0; i < 8; ++i)
; #pragma unroll
;       for (int j = 0; j < 4; ++j) acc[i][j] = mfma16(bfr[j], af[i], acc[i][j]);
;     __builtin_amdgcn_s_setprio(0);
;   }
; }
; DI void gemm8_accum(f32x4 (&acc)[8][4], const bf16_t* a, size_t lda, const bf16_t* b, size_t ldb, int nkb, bf16_t* L,
;                     const bool pre, const bf16_t* an, size_t ldan, const bf16_t* bn, size_t ldbn) {
;     ...
;   for (int kb = 0; kb + 2 < nkb; ++kb) {
;     __syncthreads();
;     g8_store1(L + ((kb + 1) & 1) * 32768, ra, lrow, lch);
;     g8_load1o(ra, a + (kb + 2) * 64, offa);
;     __builtin_amdgcn_sched_barrier(0);
;     g8_compute<0, 1>(acc, L + (kb & 1) * 32768, wm, wn, lane);
;     __builtin_amdgcn_sched_barrier(0);
;     g8_store1(L + ((kb + 1) & 1) * 32768 + 16384, rb, lrow, lch);
;     g8_load1o(rb, b + (kb + 2) * 64, offb);
;     __builtin_amdgcn_sched_barrier(0);
;     g8_compute<1, 2>(acc, L + (kb & 1) * 32768, wm, wn, lane);
;   }
.LBB0_830:
	s_add_i32 s3, s2, 0x8000
	s_and_b32 s7, s3, 0x8000
	v_lshl_add_u32 v171, s7, 1, v163
	v_lshl_add_u32 v204, s7, 1, v163
	s_waitcnt lgkmcnt(0)
	s_barrier
	s_cmp_eq_u32 s100, 0
	s_cbranch_scc1 .Lstg_830_a
	s_setprio 1
	v_mfma_f32_16x16x32_bf16 v[158:161], v[234:237], v[198:201], v[158:161]
	v_mfma_f32_16x16x32_bf16 v[154:157], v[238:241], v[198:201], v[154:157]
	v_mfma_f32_16x16x32_bf16 v[150:153], v[242:245], v[198:201], v[150:153]
	v_mfma_f32_16x16x32_bf16 v[146:149], v[246:249], v[198:201], v[146:149]
	v_mfma_f32_16x16x32_bf16 v[142:145], v[234:237], v[206:209], v[142:145]
	v_mfma_f32_16x16x32_bf16 v[138:141], v[238:241], v[206:209], v[138:141]
	v_mfma_f32_16x16x32_bf16 v[134:137], v[242:245], v[206:209], v[134:137]
	v_mfma_f32_16x16x32_bf16 v[130:133], v[246:249], v[206:209], v[130:133]
	v_mfma_f32_16x16x32_bf16 v[126:129], v[234:237], v[210:213], v[126:129]
	v_mfma_f32_16x16x32_bf16 v[122:125], v[238:241], v[210:213], v[122:125]
	v_mfma_f32_16x16x32_bf16 v[118:121], v[242:245], v[210:213], v[118:121]
	v_mfma_f32_16x16x32_bf16 v[114:117], v[246:249], v[210:213], v[114:117]
	v_mfma_f32_16x16x32_bf16 v[110:113], v[234:237], v[214:217], v[110:113]
	v_mfma_f32_16x16x32_bf16 v[106:109], v[238:241], v[214:217], v[106:109]
	v_mfma_f32_16x16x32_bf16 v[102:105], v[242:245], v[214:217], v[102:105]
	v_mfma_f32_16x16x32_bf16 v[98:101], v[246:249], v[214:217], v[98:101]
	v_mfma_f32_16x16x32_bf16 v[94:97], v[234:237], v[218:221], v[94:97]
	v_mfma_f32_16x16x32_bf16 v[90:93], v[238:241], v[218:221], v[90:93]
	v_mfma_f32_16x16x32_bf16 v[86:89], v[242:245], v[218:221], v[86:89]
	v_mfma_f32_16x16x32_bf16 v[82:85], v[246:249], v[218:221], v[82:85]
	v_mfma_f32_16x16x32_bf16 v[78:81], v[234:237], v[222:225], v[78:81]
	v_mfma_f32_16x16x32_bf16 v[74:77], v[238:241], v[222:225], v[74:77]
	v_mfma_f32_16x16x32_bf16 v[70:73], v[242:245], v[222:225], v[70:73]
	v_mfma_f32_16x16x32_bf16 v[66:69], v[246:249], v[222:225], v[66:69]
	v_mfma_f32_16x16x32_bf16 v[62:65], v[234:237], v[226:229], v[62:65]
	v_mfma_f32_16x16x32_bf16 v[58:61], v[238:241], v[226:229], v[58:61]
	v_mfma_f32_16x16x32_bf16 v[54:57], v[242:245], v[226:229], v[54:57]
	v_mfma_f32_16x16x32_bf16 v[50:53], v[246:249], v[226:229], v[50:53]
	v_mfma_f32_16x16x32_bf16 v[46:49], v[234:237], v[230:233], v[46:49]
	v_mfma_f32_16x16x32_bf16 v[42:45], v[238:241], v[230:233], v[42:45]
	v_mfma_f32_16x16x32_bf16 v[38:41], v[242:245], v[230:233], v[38:41]
	v_mfma_f32_16x16x32_bf16 v[34:37], v[246:249], v[230:233], v[34:37]
	s_setprio 0
.Lstg_830_a:
	s_and_b32 s2, s2, 0x8000
	s_lshl_b32 s2, s2, 1
	s_add_i32 s2, s2, 0
	v_lshl_add_u32 v173, v169, 1, s2
	v_add_u32_e32 v175, v173, v195
	ds_read_b128 v[198:201], v175
	ds_read_b128 v[206:209], v175 offset:2048
	ds_read_b128 v[210:213], v175 offset:4096
	ds_read_b128 v[214:217], v175 offset:6144
	ds_read_b128 v[218:221], v175 offset:8192
	ds_read_b128 v[222:225], v175 offset:10240
	ds_read_b128 v[226:229], v175 offset:12288
	ds_read_b128 v[230:233], v175 offset:14336
	v_add_u32_e32 v173, v173, v194
	ds_read_b128 v[234:237], v173 offset:32768
	ds_read_b128 v[238:241], v173 offset:34816
	ds_read_b128 v[242:245], v173 offset:36864
	ds_read_b128 v[246:249], v173 offset:38912
	s_setprio 1
	s_waitcnt lgkmcnt(3)
	v_mfma_f32_16x16x32_bf16 v[158:161], v[234:237], v[198:201], v[158:161]
	s_waitcnt lgkmcnt(2)
	v_mfma_f32_16x16x32_bf16 v[154:157], v[238:241], v[198:201], v[154:157]
	s_waitcnt lgkmcnt(1)
	v_mfma_f32_16x16x32_bf16 v[150:153], v[242:245], v[198:201], v[150:153]
	s_waitcnt lgkmcnt(0)
	s_waitcnt vmcnt(7)
	ds_write_b128 v171, v[18:21]
	s_waitcnt vmcnt(6)
	ds_write_b128 v171, v[22:25] offset:8192
	s_waitcnt vmcnt(5)
	ds_write_b128 v171, v[26:29] offset:16384
	s_waitcnt vmcnt(4)
	ds_write_b128 v171, v[30:33] offset:24576
	v_lshl_add_u64 v[18:19], v[192:193], 0, s[0:1]
	v_lshl_add_u64 v[22:23], v[190:191], 0, s[0:1]
	v_lshl_add_u64 v[26:27], v[188:189], 0, s[0:1]
	v_lshl_add_u64 v[30:31], v[186:187], 0, s[0:1]
	global_load_dwordx4 v[18:21], v[18:19], off
	s_nop 0
	global_load_dwordx4 v[22:25], v[22:23], off
	s_nop 0
	global_load_dwordx4 v[26:29], v[26:27], off
	s_nop 0
	global_load_dwordx4 v[30:33], v[30:31], off
	v_mfma_f32_16x16x32_bf16 v[146:149], v[246:249], v[198:201], v[146:149]
	v_mfma_f32_16x16x32_bf16 v[142:145], v[234:237], v[206:209], v[142:145]
	v_mfma_f32_16x16x32_bf16 v[138:141], v[238:241], v[206:209], v[138:141]
	v_mfma_f32_16x16x32_bf16 v[134:137], v[242:245], v[206:209], v[134:137]
	v_mfma_f32_16x16x32_bf16 v[130:133], v[246:249], v[206:209], v[130:133]
	v_mfma_f32_16x16x32_bf16 v[126:129], v[234:237], v[210:213], v[126:129]
	v_mfma_f32_16x16x32_bf16 v[122:125], v[238:241], v[210:213], v[122:125]
	v_mfma_f32_16x16x32_bf16 v[118:121], v[242:245], v[210:213], v[118:121]
	v_mfma_f32_16x16x32_bf16 v[114:117], v[246:249], v[210:213], v[114:117]
	v_mfma_f32_16x16x32_bf16 v[110:113], v[234:237], v[214:217], v[110:113]
	v_mfma_f32_16x16x32_bf16 v[106:109], v[238:241], v[214:217], v[106:109]
	v_mfma_f32_16x16x32_bf16 v[102:105], v[242:245], v[214:217], v[102:105]
	v_mfma_f32_16x16x32_bf16 v[98:101], v[246:249], v[214:217], v[98:101]
	v_mfma_f32_16x16x32_bf16 v[94:97], v[234:237], v[218:221], v[94:97]
	v_mfma_f32_16x16x32_bf16 v[90:93], v[238:241], v[218:221], v[90:93]
	v_mfma_f32_16x16x32_bf16 v[86:89], v[242:245], v[218:221], v[86:89]
	v_mfma_f32_16x16x32_bf16 v[82:85], v[246:249], v[218:221], v[82:85]
	v_mfma_f32_16x16x32_bf16 v[78:81], v[234:237], v[222:225], v[78:81]
	v_mfma_f32_16x16x32_bf16 v[74:77], v[238:241], v[222:225], v[74:77]
	v_mfma_f32_16x16x32_bf16 v[70:73], v[242:245], v[222:225], v[70:73]
	v_mfma_f32_16x16x32_bf16 v[66:69], v[246:249], v[222:225], v[66:69]
	v_mfma_f32_16x16x32_bf16 v[62:65], v[234:237], v[226:229], v[62:65]
	v_mfma_f32_16x16x32_bf16 v[58:61], v[238:241], v[226:229], v[58:61]
	v_mfma_f32_16x16x32_bf16 v[54:57], v[242:245], v[226:229], v[54:57]
	v_mfma_f32_16x16x32_bf16 v[50:53], v[246:249], v[226:229], v[50:53]
	v_mfma_f32_16x16x32_bf16 v[46:49], v[234:237], v[230:233], v[46:49]
	v_mfma_f32_16x16x32_bf16 v[42:45], v[238:241], v[230:233], v[42:45]
	v_mfma_f32_16x16x32_bf16 v[38:41], v[242:245], v[230:233], v[38:41]
	v_mfma_f32_16x16x32_bf16 v[34:37], v[246:249], v[230:233], v[34:37]
	s_setprio 0
	v_lshl_add_u32 v171, v205, 1, s2
	v_add_u32_e32 v173, v171, v195
	ds_read_b128 v[198:201], v173
	ds_read_b128 v[206:209], v173 offset:2048
	ds_read_b128 v[210:213], v173 offset:4096
	ds_read_b128 v[214:217], v173 offset:6144
	ds_read_b128 v[218:221], v173 offset:8192
	ds_read_b128 v[222:225], v173 offset:10240
	ds_read_b128 v[226:229], v173 offset:12288
	ds_read_b128 v[230:233], v173 offset:14336
	v_add_u32_e32 v171, v171, v194
	ds_read_b128 v[234:237], v171 offset:32768
	ds_read_b128 v[238:241], v171 offset:34816
	ds_read_b128 v[242:245], v171 offset:36864
	ds_read_b128 v[246:249], v171 offset:38912
	s_cmp_lg_u32 s101, 0
	s_cbranch_scc1 .Lstg_830_b2
; DI f32x4 mfma16(bf16x8 a, bf16x8 b, f32x4 c) { return __builtin_amdgcn_mfma_f32_16x16x32_bf16(a, b, c, 0, 0, 0); }
; #pragma unroll
;   for (int ks = KS0; ks < KS1; ++ks) {
;     bf16x8 af[8], bfr[4];
; #pragma unroll
;     for (int i = 0; i < 8; ++i) {
;       const int r = wm * 128 + i * 16 + (lane & 15);
;       af[i] = *(const bf16x8*)(S + r * 64 + (((ks * 4 + (lane >> 4)) ^ ((r >> 1) & 7)) << 3));
;     }
; #pragma unroll
;     for (int j = 0; j < 4; ++j) {
;       const int r = wn * 64 + j * 16 + (lane & 15);
;       bfr[j] = *(const bf16x8*)(S + 16384 + r * 64 + (((ks * 4 + (lane >> 4)) ^ ((r >> 1) & 7)) << 3));
;     }
;     __builtin_amdgcn_s_setprio(1);
; #pragma unroll
;     for (int i = 0; i < 8; ++i)
; #pragma unroll
;       for (int j = 0; j < 4; ++j) acc[i][j] = mfma16(bfr[j], af[i], acc[i][j]);
;     __builtin_amdgcn_s_setprio(0);
;   }
; }
; DI void gemm8_accum(f32x4 (&acc)[8][4], const bf16_t* a, size_t lda, const bf16_t* b, size_t ldb, int nkb, bf16_t* L,
;                     const bool pre, const bf16_t* an, size_t ldan, const bf16_t* bn, size_t ldbn) {
;     ...
;   for (int kb = 0; kb + 2 < nkb; ++kb) {
;     __syncthreads();
;     g8_store1(L + ((kb + 1) & 1) * 32768, ra, lrow, lch);
;     g8_load1o(ra, a + (kb + 2) * 64, offa);
;     __builtin_amdgcn_sched_barrier(0);
;     g8_compute<0, 1>(acc, L + (kb & 1) * 32768, wm, wn, lane);
;     __builtin_amdgcn_sched_barrier(0);
;     g8_store1(L + ((kb + 1) & 1) * 32768 + 16384, rb, lrow, lch);
;     g8_load1o(rb, b + (kb + 2) * 64, offb);
;     __builtin_amdgcn_sched_barrier(0);
;     g8_compute<1, 2>(acc, L + (kb & 1) * 32768, wm, wn, lane);
;   }
	s_setprio 1
	s_waitcnt lgkmcnt(3)
	v_mfma_f32_16x16x32_bf16 v[158:161], v[234:237], v[198:201], v[158:161]
	s_waitcnt lgkmcnt(2)
	v_mfma_f32_16x16x32_bf16 v[154:157], v[238:241], v[198:201], v[154:157]
	s_waitcnt lgkmcnt(1)
	v_mfma_f32_16x16x32_bf16 v[150:153], v[242:245], v[198:201], v[150:153]
	s_waitcnt lgkmcnt(0)
	s_waitcnt vmcnt(7)
	ds_write_b128 v204, v[14:17] offset:32768
	s_waitcnt vmcnt(6)
	ds_write_b128 v204, v[2:5] offset:40960
	s_waitcnt vmcnt(5)
	ds_write_b128 v204, v[6:9] offset:49152
	s_waitcnt vmcnt(4)
	ds_write_b128 v204, v[10:13] offset:57344
	v_lshl_add_u64 v[2:3], v[184:185], 0, s[0:1]
	v_lshl_add_u64 v[4:5], v[182:183], 0, s[0:1]
	v_lshl_add_u64 v[6:7], v[180:181], 0, s[0:1]
	v_lshl_add_u64 v[10:11], v[178:179], 0, s[0:1]
	global_load_dwordx4 v[14:17], v[2:3], off
	s_nop 0
	global_load_dwordx4 v[2:5], v[4:5], off
	s_nop 0
	global_load_dwordx4 v[6:9], v[6:7], off
	s_nop 0
	global_load_dwordx4 v[10:13], v[10:11], off
	v_mfma_f32_16x16x32_bf16 v[146:149], v[246:249], v[198:201], v[146:149]
	v_mfma_f32_16x16x32_bf16 v[142:145], v[234:237], v[206:209], v[142:145]
	v_mfma_f32_16x16x32_bf16 v[138:141], v[238:241], v[206:209], v[138:141]
	v_mfma_f32_16x16x32_bf16 v[134:137], v[242:245], v[206:209], v[134:137]
	v_mfma_f32_16x16x32_bf16 v[130:133], v[246:249], v[206:209], v[130:133]
	v_mfma_f32_16x16x32_bf16 v[126:129], v[234:237], v[210:213], v[126:129]
	v_mfma_f32_16x16x32_bf16 v[122:125], v[238:241], v[210:213], v[122:125]
	v_mfma_f32_16x16x32_bf16 v[118:121], v[242:245], v[210:213], v[118:121]
	v_mfma_f32_16x16x32_bf16 v[114:117], v[246:249], v[210:213], v[114:117]
	v_mfma_f32_16x16x32_bf16 v[110:113], v[234:237], v[214:217], v[110:113]
	v_mfma_f32_16x16x32_bf16 v[106:109], v[238:241], v[214:217], v[106:109]
	v_mfma_f32_16x16x32_bf16 v[102:105], v[242:245], v[214:217], v[102:105]
	v_mfma_f32_16x16x32_bf16 v[98:101], v[246:249], v[214:217], v[98:101]
	v_mfma_f32_16x16x32_bf16 v[94:97], v[234:237], v[218:221], v[94:97]
	v_mfma_f32_16x16x32_bf16 v[90:93], v[238:241], v[218:221], v[90:93]
	v_mfma_f32_16x16x32_bf16 v[86:89], v[242:245], v[218:221], v[86:89]
	v_mfma_f32_16x16x32_bf16 v[82:85], v[246:249], v[218:221], v[82:85]
	v_mfma_f32_16x16x32_bf16 v[78:81], v[234:237], v[222:225], v[78:81]
	v_mfma_f32_16x16x32_bf16 v[74:77], v[238:241], v[222:225], v[74:77]
	v_mfma_f32_16x16x32_bf16 v[70:73], v[242:245], v[222:225], v[70:73]
	v_mfma_f32_16x16x32_bf16 v[66:69], v[246:249], v[222:225], v[66:69]
	v_mfma_f32_16x16x32_bf16 v[62:65], v[234:237], v[226:229], v[62:65]
	v_mfma_f32_16x16x32_bf16 v[58:61], v[238:241], v[226:229], v[58:61]
	v_mfma_f32_16x16x32_bf16 v[54:57], v[242:245], v[226:229], v[54:57]
	v_mfma_f32_16x16x32_bf16 v[50:53], v[246:249], v[226:229], v[50:53]
	v_mfma_f32_16x16x32_bf16 v[46:49], v[234:237], v[230:233], v[46:49]
	v_mfma_f32_16x16x32_bf16 v[42:45], v[238:241], v[230:233], v[42:45]
	v_mfma_f32_16x16x32_bf16 v[38:41], v[242:245], v[230:233], v[38:41]
	v_mfma_f32_16x16x32_bf16 v[34:37], v[246:249], v[230:233], v[34:37]
	s_setprio 0
	s_branch .Lstg_830_b
.Lstg_830_b2:
	s_waitcnt vmcnt(7)
	ds_write_b128 v204, v[14:17] offset:32768
	s_waitcnt vmcnt(6)
	ds_write_b128 v204, v[2:5] offset:40960
	s_waitcnt vmcnt(5)
	ds_write_b128 v204, v[6:9] offset:49152
	s_waitcnt vmcnt(4)
	ds_write_b128 v204, v[10:13] offset:57344
	v_lshl_add_u64 v[2:3], v[184:185], 0, s[0:1]
	v_lshl_add_u64 v[4:5], v[182:183], 0, s[0:1]
	v_lshl_add_u64 v[6:7], v[180:181], 0, s[0:1]
	v_lshl_add_u64 v[10:11], v[178:179], 0, s[0:1]
	global_load_dwordx4 v[14:17], v[2:3], off
	s_nop 0
	global_load_dwordx4 v[2:5], v[4:5], off
	s_nop 0
	global_load_dwordx4 v[6:9], v[6:7], off
	s_nop 0
	global_load_dwordx4 v[10:13], v[10:11], off

; DI f32x4 mfma16(bf16x8 a, bf16x8 b, f32x4 c) { return __builtin_amdgcn_mfma_f32_16x16x32_bf16(a, b, c, 0, 0, 0); }
; #pragma unroll
;   for (int ks = KS0; ks < KS1; ++ks) {
;     bf16x8 af[8], bfr[4];
; #pragma unroll
;     for (int i = 0; i < 8; ++i) {
;       const int r = wm * 128 + i * 16 + (lane & 15);
;       af[i] = *(const bf16x8*)(S + r * 64 + (((ks * 4 + (lane >> 4)) ^ ((r >> 1) & 7)) << 3));
;     }
; #pragma unroll
;     for (int j = 0; j < 4; ++j) {
;       const int r = wn * 64 + j * 16 + (lane & 15);
;       bfr[j] = *(const bf16x8*)(S + 16384 + r * 64 + (((ks * 4 + (lane >> 4)) ^ ((r >> 1) & 7)) << 3));
;     }
;     __builtin_amdgcn_s_setprio(1);
; #pragma unroll
;     for (int i = 0; i < 8; ++i)
; #pragma unroll
;       for (int j = 0; j < 4; ++j) acc[i][j] = mfma16(bfr[j], af[i], acc[i][j]);
;     __builtin_amdgcn_s_setprio(0);
;   }
; }
; DI void gemm8_accum(f32x4 (&acc)[8][4], const bf16_t* a, size_t lda, const bf16_t* b, size_t ldb, int nkb, bf16_t* L,
;                     const bool pre, const bf16_t* an, size_t ldan, const bf16_t* bn, size_t ldbn) {
;     ...
;   for (int kb = 0; kb + 2 < nkb; ++kb) {
;     __syncthreads();
;     g8_store1(L + ((kb + 1) & 1) * 32768, ra, lrow, lch);
;     g8_load1o(ra, a + (kb + 2) * 64, offa);
;     __builtin_amdgcn_sched_barrier(0);
;     g8_compute<0, 1>(acc, L + (kb & 1) * 32768, wm, wn, lane);
;     __builtin_amdgcn_sched_barrier(0);
;     g8_store1(L + ((kb + 1) & 1) * 32768 + 16384, rb, lrow, lch);
;     g8_load1o(rb, b + (kb + 2) * 64, offb);
;     __builtin_amdgcn_sched_barrier(0);
;     g8_compute<1, 2>(acc, L + (kb & 1) * 32768, wm, wn, lane);
;   }
.LBB0_892:
	s_add_i32 s3, s2, 0x8000
	s_and_b32 s6, s3, 0x8000
	v_lshl_add_u32 v167, s6, 1, v163
	v_lshl_add_u32 v204, s6, 1, v163
	s_waitcnt lgkmcnt(0)
	s_barrier
	s_cmp_eq_u32 s100, 0
	s_cbranch_scc1 .Lstg_892_a
	s_setprio 1
	v_mfma_f32_16x16x32_bf16 v[158:161], v[230:233], v[192:195], v[158:161]
	v_mfma_f32_16x16x32_bf16 v[154:157], v[234:237], v[192:195], v[154:157]
	v_mfma_f32_16x16x32_bf16 v[150:153], v[238:241], v[192:195], v[150:153]
	v_mfma_f32_16x16x32_bf16 v[146:149], v[242:245], v[192:195], v[146:149]
	v_mfma_f32_16x16x32_bf16 v[142:145], v[230:233], v[198:201], v[142:145]
	v_mfma_f32_16x16x32_bf16 v[138:141], v[234:237], v[198:201], v[138:141]
	v_mfma_f32_16x16x32_bf16 v[134:137], v[238:241], v[198:201], v[134:137]
	v_mfma_f32_16x16x32_bf16 v[130:133], v[242:245], v[198:201], v[130:133]
	v_mfma_f32_16x16x32_bf16 v[126:129], v[230:233], v[206:209], v[126:129]
	v_mfma_f32_16x16x32_bf16 v[122:125], v[234:237], v[206:209], v[122:125]
	v_mfma_f32_16x16x32_bf16 v[118:121], v[238:241], v[206:209], v[118:121]
	v_mfma_f32_16x16x32_bf16 v[114:117], v[242:245], v[206:209], v[114:117]
	v_mfma_f32_16x16x32_bf16 v[110:113], v[230:233], v[210:213], v[110:113]
	v_mfma_f32_16x16x32_bf16 v[106:109], v[234:237], v[210:213], v[106:109]
	v_mfma_f32_16x16x32_bf16 v[102:105], v[238:241], v[210:213], v[102:105]
	v_mfma_f32_16x16x32_bf16 v[98:101], v[242:245], v[210:213], v[98:101]
	v_mfma_f32_16x16x32_bf16 v[94:97], v[230:233], v[214:217], v[94:97]
	v_mfma_f32_16x16x32_bf16 v[90:93], v[234:237], v[214:217], v[90:93]
	v_mfma_f32_16x16x32_bf16 v[86:89], v[238:241], v[214:217], v[86:89]
	v_mfma_f32_16x16x32_bf16 v[82:85], v[242:245], v[214:217], v[82:85]
	v_mfma_f32_16x16x32_bf16 v[78:81], v[230:233], v[218:221], v[78:81]
	v_mfma_f32_16x16x32_bf16 v[74:77], v[234:237], v[218:221], v[74:77]
	v_mfma_f32_16x16x32_bf16 v[70:73], v[238:241], v[218:221], v[70:73]
	v_mfma_f32_16x16x32_bf16 v[66:69], v[242:245], v[218:221], v[66:69]
	v_mfma_f32_16x16x32_bf16 v[62:65], v[230:233], v[222:225], v[62:65]
	v_mfma_f32_16x16x32_bf16 v[58:61], v[234:237], v[222:225], v[58:61]
	v_mfma_f32_16x16x32_bf16 v[54:57], v[238:241], v[222:225], v[54:57]
	v_mfma_f32_16x16x32_bf16 v[50:53], v[242:245], v[222:225], v[50:53]
	v_mfma_f32_16x16x32_bf16 v[46:49], v[230:233], v[226:229], v[46:49]
	v_mfma_f32_16x16x32_bf16 v[42:45], v[234:237], v[226:229], v[42:45]
	v_mfma_f32_16x16x32_bf16 v[38:41], v[238:241], v[226:229], v[38:41]
	v_mfma_f32_16x16x32_bf16 v[34:37], v[242:245], v[226:229], v[34:37]
	s_setprio 0
.Lstg_892_a:
	s_and_b32 s2, s2, 0x8000
	s_lshl_b32 s2, s2, 1
	s_add_i32 s2, s2, 0
	v_lshl_add_u32 v169, v191, 1, s2
	v_add_u32_e32 v202, v169, v187
	ds_read_b128 v[192:195], v202
	ds_read_b128 v[198:201], v202 offset:2048
	ds_read_b128 v[206:209], v202 offset:4096
	ds_read_b128 v[210:213], v202 offset:6144
	ds_read_b128 v[214:217], v202 offset:8192
	ds_read_b128 v[218:221], v202 offset:10240
	ds_read_b128 v[222:225], v202 offset:12288
	ds_read_b128 v[226:229], v202 offset:14336
	v_add_u32_e32 v169, v169, v186
	ds_read_b128 v[230:233], v169 offset:32768
	ds_read_b128 v[234:237], v169 offset:34816
	ds_read_b128 v[238:241], v169 offset:36864
	ds_read_b128 v[242:245], v169 offset:38912
	s_setprio 1
	s_waitcnt lgkmcnt(3)
	v_mfma_f32_16x16x32_bf16 v[158:161], v[230:233], v[192:195], v[158:161]
	s_waitcnt lgkmcnt(2)
	v_mfma_f32_16x16x32_bf16 v[154:157], v[234:237], v[192:195], v[154:157]
	s_waitcnt lgkmcnt(1)
	v_mfma_f32_16x16x32_bf16 v[150:153], v[238:241], v[192:195], v[150:153]
	s_waitcnt lgkmcnt(0)
	s_waitcnt vmcnt(5)
	ds_write_b128 v167, v[22:25]
	ds_write_b128 v167, v[18:21] offset:8192
	ds_write_b128 v167, v[26:29] offset:16384
	s_waitcnt vmcnt(4)
	ds_write_b128 v167, v[30:33] offset:24576
	v_lshl_add_u64 v[18:19], v[184:185], 0, s[0:1]
	v_lshl_add_u64 v[26:27], v[180:181], 0, s[0:1]
	global_load_dwordx4 v[22:25], v[18:19], off
	v_lshl_add_u64 v[30:31], v[178:179], 0, s[0:1]
	global_load_dwordx4 v[26:29], v[26:27], off
	v_lshl_add_u64 v[18:19], v[182:183], 0, s[0:1]
	global_load_dwordx4 v[18:21], v[18:19], off
	s_nop 0
	global_load_dwordx4 v[30:33], v[30:31], off
	v_mfma_f32_16x16x32_bf16 v[146:149], v[242:245], v[192:195], v[146:149]
	v_mfma_f32_16x16x32_bf16 v[142:145], v[230:233], v[198:201], v[142:145]
	v_mfma_f32_16x16x32_bf16 v[138:141], v[234:237], v[198:201], v[138:141]
	v_mfma_f32_16x16x32_bf16 v[134:137], v[238:241], v[198:201], v[134:137]
	v_mfma_f32_16x16x32_bf16 v[130:133], v[242:245], v[198:201], v[130:133]
	v_mfma_f32_16x16x32_bf16 v[126:129], v[230:233], v[206:209], v[126:129]
	v_mfma_f32_16x16x32_bf16 v[122:125], v[234:237], v[206:209], v[122:125]
	v_mfma_f32_16x16x32_bf16 v[118:121], v[238:241], v[206:209], v[118:121]
	v_mfma_f32_16x16x32_bf16 v[114:117], v[242:245], v[206:209], v[114:117]
	v_mfma_f32_16x16x32_bf16 v[110:113], v[230:233], v[210:213], v[110:113]
	v_mfma_f32_16x16x32_bf16 v[106:109], v[234:237], v[210:213], v[106:109]
	v_mfma_f32_16x16x32_bf16 v[102:105], v[238:241], v[210:213], v[102:105]
	v_mfma_f32_16x16x32_bf16 v[98:101], v[242:245], v[210:213], v[98:101]
	v_mfma_f32_16x16x32_bf16 v[94:97], v[230:233], v[214:217], v[94:97]
	v_mfma_f32_16x16x32_bf16 v[90:93], v[234:237], v[214:217], v[90:93]
	v_mfma_f32_16x16x32_bf16 v[86:89], v[238:241], v[214:217], v[86:89]
	v_mfma_f32_16x16x32_bf16 v[82:85], v[242:245], v[214:217], v[82:85]
	v_mfma_f32_16x16x32_bf16 v[78:81], v[230:233], v[218:221], v[78:81]
	v_mfma_f32_16x16x32_bf16 v[74:77], v[234:237], v[218:221], v[74:77]
	v_mfma_f32_16x16x32_bf16 v[70:73], v[238:241], v[218:221], v[70:73]
	v_mfma_f32_16x16x32_bf16 v[66:69], v[242:245], v[218:221], v[66:69]
	v_mfma_f32_16x16x32_bf16 v[62:65], v[230:233], v[222:225], v[62:65]
	v_mfma_f32_16x16x32_bf16 v[58:61], v[234:237], v[222:225], v[58:61]
	v_mfma_f32_16x16x32_bf16 v[54:57], v[238:241], v[222:225], v[54:57]
	v_mfma_f32_16x16x32_bf16 v[50:53], v[242:245], v[222:225], v[50:53]
	v_mfma_f32_16x16x32_bf16 v[46:49], v[230:233], v[226:229], v[46:49]
	v_mfma_f32_16x16x32_bf16 v[42:45], v[234:237], v[226:229], v[42:45]
	v_mfma_f32_16x16x32_bf16 v[38:41], v[238:241], v[226:229], v[38:41]
	v_mfma_f32_16x16x32_bf16 v[34:37], v[242:245], v[226:229], v[34:37]
	s_setprio 0
	v_lshl_add_u32 v167, v188, 1, s2
	v_add_u32_e32 v169, v167, v187
	ds_read_b128 v[192:195], v169
	ds_read_b128 v[198:201], v169 offset:2048
	ds_read_b128 v[206:209], v169 offset:4096
	ds_read_b128 v[210:213], v169 offset:6144
	ds_read_b128 v[214:217], v169 offset:8192
	ds_read_b128 v[218:221], v169 offset:10240
	ds_read_b128 v[222:225], v169 offset:12288
	ds_read_b128 v[226:229], v169 offset:14336
	v_add_u32_e32 v167, v167, v186
	ds_read_b128 v[230:233], v167 offset:32768
	ds_read_b128 v[234:237], v167 offset:34816
	ds_read_b128 v[238:241], v167 offset:36864
	ds_read_b128 v[242:245], v167 offset:38912
	s_cmp_lg_u32 s101, 0
	s_cbranch_scc1 .Lstg_892_b2
; DI f32x4 mfma16(bf16x8 a, bf16x8 b, f32x4 c) { return __builtin_amdgcn_mfma_f32_16x16x32_bf16(a, b, c, 0, 0, 0); }
; #pragma unroll
;   for (int ks = KS0; ks < KS1; ++ks) {
;     bf16x8 af[8], bfr[4];
; #pragma unroll
;     for (int i = 0; i < 8; ++i) {
;       const int r = wm * 128 + i * 16 + (lane & 15);
;       af[i] = *(const bf16x8*)(S + r * 64 + (((ks * 4 + (lane >> 4)) ^ ((r >> 1) & 7)) << 3));
;     }
; #pragma unroll
;     for (int j = 0; j < 4; ++j) {
;       const int r = wn * 64 + j * 16 + (lane & 15);
;       bfr[j] = *(const bf16x8*)(S + 16384 + r * 64 + (((ks * 4 + (lane >> 4)) ^ ((r >> 1) & 7)) << 3));
;     }
;     __builtin_amdgcn_s_setprio(1);
; #pragma unroll
;     for (int i = 0; i < 8; ++i)
; #pragma unroll
;       for (int j = 0; j < 4; ++j) acc[i][j] = mfma16(bfr[j], af[i], acc[i][j]);
;     __builtin_amdgcn_s_setprio(0);
;   }
; }
; DI void gemm8_accum(f32x4 (&acc)[8][4], const bf16_t* a, size_t lda, const bf16_t* b, size_t ldb, int nkb, bf16_t* L,
;                     const bool pre, const bf16_t* an, size_t ldan, const bf16_t* bn, size_t ldbn) {
;     ...
;   for (int kb = 0; kb + 2 < nkb; ++kb) {
;     __syncthreads();
;     g8_store1(L + ((kb + 1) & 1) * 32768, ra, lrow, lch);
;     g8_load1o(ra, a + (kb + 2) * 64, offa);
;     __builtin_amdgcn_sched_barrier(0);
;     g8_compute<0, 1>(acc, L + (kb & 1) * 32768, wm, wn, lane);
;     __builtin_amdgcn_sched_barrier(0);
;     g8_store1(L + ((kb + 1) & 1) * 32768 + 16384, rb, lrow, lch);
;     g8_load1o(rb, b + (kb + 2) * 64, offb);
;     __builtin_amdgcn_sched_barrier(0);
;     g8_compute<1, 2>(acc, L + (kb & 1) * 32768, wm, wn, lane);
;   }
	s_setprio 1
	s_waitcnt lgkmcnt(3)
	v_mfma_f32_16x16x32_bf16 v[158:161], v[230:233], v[192:195], v[158:161]
	s_waitcnt lgkmcnt(2)
	v_mfma_f32_16x16x32_bf16 v[154:157], v[234:237], v[192:195], v[154:157]
	s_waitcnt lgkmcnt(1)
	v_mfma_f32_16x16x32_bf16 v[150:153], v[238:241], v[192:195], v[150:153]
	s_waitcnt lgkmcnt(0)
	s_waitcnt vmcnt(7)
	ds_write_b128 v204, v[14:17] offset:32768
	s_waitcnt vmcnt(6)
	ds_write_b128 v204, v[2:5] offset:40960
	s_waitcnt vmcnt(5)
	ds_write_b128 v204, v[6:9] offset:49152
	s_waitcnt vmcnt(4)
	ds_write_b128 v204, v[10:13] offset:57344
	v_lshl_add_u64 v[2:3], v[176:177], 0, s[0:1]
	v_lshl_add_u64 v[4:5], v[174:175], 0, s[0:1]
	v_lshl_add_u64 v[6:7], v[172:173], 0, s[0:1]
	v_lshl_add_u64 v[10:11], v[170:171], 0, s[0:1]
	global_load_dwordx4 v[14:17], v[2:3], off
	s_nop 0
	global_load_dwordx4 v[2:5], v[4:5], off
	s_nop 0
	global_load_dwordx4 v[6:9], v[6:7], off
	s_nop 0
	global_load_dwordx4 v[10:13], v[10:11], off
	v_mfma_f32_16x16x32_bf16 v[146:149], v[242:245], v[192:195], v[146:149]
	v_mfma_f32_16x16x32_bf16 v[142:145], v[230:233], v[198:201], v[142:145]
	v_mfma_f32_16x16x32_bf16 v[138:141], v[234:237], v[198:201], v[138:141]
	v_mfma_f32_16x16x32_bf16 v[134:137], v[238:241], v[198:201], v[134:137]
	v_mfma_f32_16x16x32_bf16 v[130:133], v[242:245], v[198:201], v[130:133]
	v_mfma_f32_16x16x32_bf16 v[126:129], v[230:233], v[206:209], v[126:129]
	v_mfma_f32_16x16x32_bf16 v[122:125], v[234:237], v[206:209], v[122:125]
	v_mfma_f32_16x16x32_bf16 v[118:121], v[238:241], v[206:209], v[118:121]
	v_mfma_f32_16x16x32_bf16 v[114:117], v[242:245], v[206:209], v[114:117]
	v_mfma_f32_16x16x32_bf16 v[110:113], v[230:233], v[210:213], v[110:113]
	v_mfma_f32_16x16x32_bf16 v[106:109], v[234:237], v[210:213], v[106:109]
	v_mfma_f32_16x16x32_bf16 v[102:105], v[238:241], v[210:213], v[102:105]
	v_mfma_f32_16x16x32_bf16 v[98:101], v[242:245], v[210:213], v[98:101]
	v_mfma_f32_16x16x32_bf16 v[94:97], v[230:233], v[214:217], v[94:97]
	v_mfma_f32_16x16x32_bf16 v[90:93], v[234:237], v[214:217], v[90:93]
	v_mfma_f32_16x16x32_bf16 v[86:89], v[238:241], v[214:217], v[86:89]
	v_mfma_f32_16x16x32_bf16 v[82:85], v[242:245], v[214:217], v[82:85]
	v_mfma_f32_16x16x32_bf16 v[78:81], v[230:233], v[218:221], v[78:81]
	v_mfma_f32_16x16x32_bf16 v[74:77], v[234:237], v[218:221], v[74:77]
	v_mfma_f32_16x16x32_bf16 v[70:73], v[238:241], v[218:221], v[70:73]
	v_mfma_f32_16x16x32_bf16 v[66:69], v[242:245], v[218:221], v[66:69]
	v_mfma_f32_16x16x32_bf16 v[62:65], v[230:233], v[222:225], v[62:65]
	v_mfma_f32_16x16x32_bf16 v[58:61], v[234:237], v[222:225], v[58:61]
	v_mfma_f32_16x16x32_bf16 v[54:57], v[238:241], v[222:225], v[54:57]
	v_mfma_f32_16x16x32_bf16 v[50:53], v[242:245], v[222:225], v[50:53]
	v_mfma_f32_16x16x32_bf16 v[46:49], v[230:233], v[226:229], v[46:49]
	v_mfma_f32_16x16x32_bf16 v[42:45], v[234:237], v[226:229], v[42:45]
	v_mfma_f32_16x16x32_bf16 v[38:41], v[238:241], v[226:229], v[38:41]
	v_mfma_f32_16x16x32_bf16 v[34:37], v[242:245], v[226:229], v[34:37]
	s_setprio 0
	s_branch .Lstg_892_b
.Lstg_892_b2:
	s_waitcnt vmcnt(7)
	ds_write_b128 v204, v[14:17] offset:32768
	s_waitcnt vmcnt(6)
	ds_write_b128 v204, v[2:5] offset:40960
	s_waitcnt vmcnt(5)
	ds_write_b128 v204, v[6:9] offset:49152
	s_waitcnt vmcnt(4)
	ds_write_b128 v204, v[10:13] offset:57344
	v_lshl_add_u64 v[2:3], v[176:177], 0, s[0:1]
	v_lshl_add_u64 v[4:5], v[174:175], 0, s[0:1]
	v_lshl_add_u64 v[6:7], v[172:173], 0, s[0:1]
	v_lshl_add_u64 v[10:11], v[170:171], 0, s[0:1]
	global_load_dwordx4 v[14:17], v[2:3], off
	s_nop 0
	global_load_dwordx4 v[2:5], v[4:5], off
	s_nop 0
	global_load_dwordx4 v[6:9], v[6:7], off
	s_nop 0
	global_load_dwordx4 v[10:13], v[10:11], off

; DI f32x4 mfma16(bf16x8 a, bf16x8 b, f32x4 c) { return __builtin_amdgcn_mfma_f32_16x16x32_bf16(a, b, c, 0, 0, 0); }
; #pragma unroll
;   for (int ks = KS0; ks < KS1; ++ks) {
;     bf16x8 af[8], bfr[4];
; #pragma unroll
;     for (int i = 0; i < 8; ++i) {
;       const int r = wm * 128 + i * 16 + (lane & 15);
;       af[i] = *(const bf16x8*)(S + r * 64 + (((ks * 4 + (lane >> 4)) ^ ((r >> 1) & 7)) << 3));
;     }
; #pragma unroll
;     for (int j = 0; j < 4; ++j) {
;       const int r = wn * 64 + j * 16 + (lane & 15);
;       bfr[j] = *(const bf16x8*)(S + 16384 + r * 64 + (((ks * 4 + (lane >> 4)) ^ ((r >> 1) & 7)) << 3));
;     }
;     __builtin_amdgcn_s_setprio(1);
; #pragma unroll
;     for (int i = 0; i < 8; ++i)
; #pragma unroll
;       for (int j = 0; j < 4; ++j) acc[i][j] = mfma16(bfr[j], af[i], acc[i][j]);
;     __builtin_amdgcn_s_setprio(0);
;   }
; }
; DI void gemm8_accum(f32x4 (&acc)[8][4], const bf16_t* a, size_t lda, const bf16_t* b, size_t ldb, int nkb, bf16_t* L,
;                     const bool pre, const bf16_t* an, size_t ldan, const bf16_t* bn, size_t ldbn) {
;     ...
;   for (int kb = 0; kb + 2 < nkb; ++kb) {
;     __syncthreads();
;     g8_store1(L + ((kb + 1) & 1) * 32768, ra, lrow, lch);
;     g8_load1o(ra, a + (kb + 2) * 64, offa);
;     __builtin_amdgcn_sched_barrier(0);
;     g8_compute<0, 1>(acc, L + (kb & 1) * 32768, wm, wn, lane);
;     __builtin_amdgcn_sched_barrier(0);
;     g8_store1(L + ((kb + 1) & 1) * 32768 + 16384, rb, lrow, lch);
;     g8_load1o(rb, b + (kb + 2) * 64, offb);
;     __builtin_amdgcn_sched_barrier(0);
;     g8_compute<1, 2>(acc, L + (kb & 1) * 32768, wm, wn, lane);
;   }
.LBB0_942:
	s_add_i32 s3, s2, 0x8000
	s_and_b32 s7, s3, 0x8000
	v_lshl_add_u32 v167, s7, 1, v163
	v_lshl_add_u32 v246, s7, 1, v163
	s_waitcnt lgkmcnt(0)
	s_barrier
	s_cmp_eq_u32 s100, 0
	s_cbranch_scc1 .Lstg_942_a
	s_setprio 1
	v_mfma_f32_16x16x32_bf16 v[158:161], v[226:229], v[192:195], v[158:161]
	v_mfma_f32_16x16x32_bf16 v[154:157], v[230:233], v[192:195], v[154:157]
	v_mfma_f32_16x16x32_bf16 v[150:153], v[234:237], v[192:195], v[150:153]
	v_mfma_f32_16x16x32_bf16 v[146:149], v[238:241], v[192:195], v[146:149]
	v_mfma_f32_16x16x32_bf16 v[142:145], v[226:229], v[198:201], v[142:145]
	v_mfma_f32_16x16x32_bf16 v[138:141], v[230:233], v[198:201], v[138:141]
	v_mfma_f32_16x16x32_bf16 v[134:137], v[234:237], v[198:201], v[134:137]
	v_mfma_f32_16x16x32_bf16 v[130:133], v[238:241], v[198:201], v[130:133]
	v_mfma_f32_16x16x32_bf16 v[126:129], v[226:229], v[202:205], v[126:129]
	v_mfma_f32_16x16x32_bf16 v[122:125], v[230:233], v[202:205], v[122:125]
	v_mfma_f32_16x16x32_bf16 v[118:121], v[234:237], v[202:205], v[118:121]
	v_mfma_f32_16x16x32_bf16 v[114:117], v[238:241], v[202:205], v[114:117]
	v_mfma_f32_16x16x32_bf16 v[110:113], v[226:229], v[206:209], v[110:113]
	v_mfma_f32_16x16x32_bf16 v[106:109], v[230:233], v[206:209], v[106:109]
	v_mfma_f32_16x16x32_bf16 v[102:105], v[234:237], v[206:209], v[102:105]
	v_mfma_f32_16x16x32_bf16 v[98:101], v[238:241], v[206:209], v[98:101]
	v_mfma_f32_16x16x32_bf16 v[94:97], v[226:229], v[210:213], v[94:97]
	v_mfma_f32_16x16x32_bf16 v[90:93], v[230:233], v[210:213], v[90:93]
	v_mfma_f32_16x16x32_bf16 v[86:89], v[234:237], v[210:213], v[86:89]
	v_mfma_f32_16x16x32_bf16 v[82:85], v[238:241], v[210:213], v[82:85]
	v_mfma_f32_16x16x32_bf16 v[78:81], v[226:229], v[214:217], v[78:81]
	v_mfma_f32_16x16x32_bf16 v[74:77], v[230:233], v[214:217], v[74:77]
	v_mfma_f32_16x16x32_bf16 v[70:73], v[234:237], v[214:217], v[70:73]
	v_mfma_f32_16x16x32_bf16 v[66:69], v[238:241], v[214:217], v[66:69]
	v_mfma_f32_16x16x32_bf16 v[62:65], v[226:229], v[218:221], v[62:65]
	v_mfma_f32_16x16x32_bf16 v[58:61], v[230:233], v[218:221], v[58:61]
	v_mfma_f32_16x16x32_bf16 v[54:57], v[234:237], v[218:221], v[54:57]
	v_mfma_f32_16x16x32_bf16 v[50:53], v[238:241], v[218:221], v[50:53]
	v_mfma_f32_16x16x32_bf16 v[46:49], v[226:229], v[222:225], v[46:49]
	v_mfma_f32_16x16x32_bf16 v[42:45], v[230:233], v[222:225], v[42:45]
	v_mfma_f32_16x16x32_bf16 v[38:41], v[234:237], v[222:225], v[38:41]
	v_mfma_f32_16x16x32_bf16 v[34:37], v[238:241], v[222:225], v[34:37]
	s_setprio 0
.Lstg_942_a:
	s_and_b32 s2, s2, 0x8000
	s_lshl_b32 s2, s2, 1
	s_add_i32 s2, s2, 0
	v_lshl_add_u32 v169, v191, 1, s2
	v_add_u32_e32 v222, v169, v187
	ds_read_b128 v[192:195], v222
	ds_read_b128 v[198:201], v222 offset:2048
	ds_read_b128 v[202:205], v222 offset:4096
	ds_read_b128 v[206:209], v222 offset:6144
	ds_read_b128 v[210:213], v222 offset:8192
	ds_read_b128 v[214:217], v222 offset:10240
	ds_read_b128 v[218:221], v222 offset:12288
	ds_read_b128 v[222:225], v222 offset:14336
	v_add_u32_e32 v169, v169, v186
	ds_read_b128 v[226:229], v169 offset:32768
	ds_read_b128 v[230:233], v169 offset:34816
	ds_read_b128 v[234:237], v169 offset:36864
	ds_read_b128 v[238:241], v169 offset:38912
	s_setprio 1
	s_waitcnt lgkmcnt(3)
	v_mfma_f32_16x16x32_bf16 v[158:161], v[226:229], v[192:195], v[158:161]
	s_waitcnt lgkmcnt(2)
	v_mfma_f32_16x16x32_bf16 v[154:157], v[230:233], v[192:195], v[154:157]
	s_waitcnt lgkmcnt(1)
	v_mfma_f32_16x16x32_bf16 v[150:153], v[234:237], v[192:195], v[150:153]
	s_waitcnt lgkmcnt(0)
	s_waitcnt vmcnt(5)
	ds_write_b128 v167, v[22:25]
	ds_write_b128 v167, v[18:21] offset:8192
	ds_write_b128 v167, v[26:29] offset:16384
	s_waitcnt vmcnt(4)
	ds_write_b128 v167, v[30:33] offset:24576
	v_lshl_add_u64 v[18:19], v[184:185], 0, s[0:1]
	v_lshl_add_u64 v[26:27], v[180:181], 0, s[0:1]
	global_load_dwordx4 v[22:25], v[18:19], off
	v_lshl_add_u64 v[30:31], v[178:179], 0, s[0:1]
	global_load_dwordx4 v[26:29], v[26:27], off
	v_lshl_add_u64 v[18:19], v[182:183], 0, s[0:1]
	global_load_dwordx4 v[18:21], v[18:19], off
	s_nop 0
	global_load_dwordx4 v[30:33], v[30:31], off
	v_mfma_f32_16x16x32_bf16 v[146:149], v[238:241], v[192:195], v[146:149]
	v_mfma_f32_16x16x32_bf16 v[142:145], v[226:229], v[198:201], v[142:145]
	v_mfma_f32_16x16x32_bf16 v[138:141], v[230:233], v[198:201], v[138:141]
	v_mfma_f32_16x16x32_bf16 v[134:137], v[234:237], v[198:201], v[134:137]
	v_mfma_f32_16x16x32_bf16 v[130:133], v[238:241], v[198:201], v[130:133]
	v_mfma_f32_16x16x32_bf16 v[126:129], v[226:229], v[202:205], v[126:129]
	v_mfma_f32_16x16x32_bf16 v[122:125], v[230:233], v[202:205], v[122:125]
	v_mfma_f32_16x16x32_bf16 v[118:121], v[234:237], v[202:205], v[118:121]
	v_mfma_f32_16x16x32_bf16 v[114:117], v[238:241], v[202:205], v[114:117]
	v_mfma_f32_16x16x32_bf16 v[110:113], v[226:229], v[206:209], v[110:113]
	v_mfma_f32_16x16x32_bf16 v[106:109], v[230:233], v[206:209], v[106:109]
	v_mfma_f32_16x16x32_bf16 v[102:105], v[234:237], v[206:209], v[102:105]
	v_mfma_f32_16x16x32_bf16 v[98:101], v[238:241], v[206:209], v[98:101]
	v_mfma_f32_16x16x32_bf16 v[94:97], v[226:229], v[210:213], v[94:97]
	v_mfma_f32_16x16x32_bf16 v[90:93], v[230:233], v[210:213], v[90:93]
	v_mfma_f32_16x16x32_bf16 v[86:89], v[234:237], v[210:213], v[86:89]
	v_mfma_f32_16x16x32_bf16 v[82:85], v[238:241], v[210:213], v[82:85]
	v_mfma_f32_16x16x32_bf16 v[78:81], v[226:229], v[214:217], v[78:81]
	v_mfma_f32_16x16x32_bf16 v[74:77], v[230:233], v[214:217], v[74:77]
	v_mfma_f32_16x16x32_bf16 v[70:73], v[234:237], v[214:217], v[70:73]
	v_mfma_f32_16x16x32_bf16 v[66:69], v[238:241], v[214:217], v[66:69]
	v_mfma_f32_16x16x32_bf16 v[62:65], v[226:229], v[218:221], v[62:65]
	v_mfma_f32_16x16x32_bf16 v[58:61], v[230:233], v[218:221], v[58:61]
	v_mfma_f32_16x16x32_bf16 v[54:57], v[234:237], v[218:221], v[54:57]
	v_mfma_f32_16x16x32_bf16 v[50:53], v[238:241], v[218:221], v[50:53]
	v_mfma_f32_16x16x32_bf16 v[46:49], v[226:229], v[222:225], v[46:49]
	v_mfma_f32_16x16x32_bf16 v[42:45], v[230:233], v[222:225], v[42:45]
	v_mfma_f32_16x16x32_bf16 v[38:41], v[234:237], v[222:225], v[38:41]
	v_mfma_f32_16x16x32_bf16 v[34:37], v[238:241], v[222:225], v[34:37]
	s_setprio 0
	v_lshl_add_u32 v167, v188, 1, s2
	v_add_u32_e32 v169, v167, v187
	ds_read_b128 v[192:195], v169
	ds_read_b128 v[198:201], v169 offset:2048
	ds_read_b128 v[202:205], v169 offset:4096
	ds_read_b128 v[206:209], v169 offset:6144
	ds_read_b128 v[210:213], v169 offset:8192
	ds_read_b128 v[214:217], v169 offset:10240
	ds_read_b128 v[218:221], v169 offset:12288
	ds_read_b128 v[222:225], v169 offset:14336
	v_add_u32_e32 v167, v167, v186
	ds_read_b128 v[226:229], v167 offset:32768
	ds_read_b128 v[230:233], v167 offset:34816
	ds_read_b128 v[234:237], v167 offset:36864
	ds_read_b128 v[238:241], v167 offset:38912
	s_cmp_lg_u32 s101, 0
	s_cbranch_scc1 .Lstg_942_b2
; DI f32x4 mfma16(bf16x8 a, bf16x8 b, f32x4 c) { return __builtin_amdgcn_mfma_f32_16x16x32_bf16(a, b, c, 0, 0, 0); }
; #pragma unroll
;   for (int ks = KS0; ks < KS1; ++ks) {
;     bf16x8 af[8], bfr[4];
; #pragma unroll
;     for (int i = 0; i < 8; ++i) {
;       const int r = wm * 128 + i * 16 + (lane & 15);
;       af[i] = *(const bf16x8*)(S + r * 64 + (((ks * 4 + (lane >> 4)) ^ ((r >> 1) & 7)) << 3));
;     }
; #pragma unroll
;     for (int j = 0; j < 4; ++j) {
;       const int r = wn * 64 + j * 16 + (lane & 15);
;       bfr[j] = *(const bf16x8*)(S + 16384 + r * 64 + (((ks * 4 + (lane >> 4)) ^ ((r >> 1) & 7)) << 3));
;     }
;     __builtin_amdgcn_s_setprio(1);
; #pragma unroll
;     for (int i = 0; i < 8; ++i)
; #pragma unroll
;       for (int j = 0; j < 4; ++j) acc[i][j] = mfma16(bfr[j], af[i], acc[i][j]);
;     __builtin_amdgcn_s_setprio(0);
;   }
; }
; DI void gemm8_accum(f32x4 (&acc)[8][4], const bf16_t* a, size_t lda, const bf16_t* b, size_t ldb, int nkb, bf16_t* L,
;                     const bool pre, const bf16_t* an, size_t ldan, const bf16_t* bn, size_t ldbn) {
;     ...
;   for (int kb = 0; kb + 2 < nkb; ++kb) {
;     __syncthreads();
;     g8_store1(L + ((kb + 1) & 1) * 32768, ra, lrow, lch);
;     g8_load1o(ra, a + (kb + 2) * 64, offa);
;     __builtin_amdgcn_sched_barrier(0);
;     g8_compute<0, 1>(acc, L + (kb & 1) * 32768, wm, wn, lane);
;     __builtin_amdgcn_sched_barrier(0);
;     g8_store1(L + ((kb + 1) & 1) * 32768 + 16384, rb, lrow, lch);
;     g8_load1o(rb, b + (kb + 2) * 64, offb);
;     __builtin_amdgcn_sched_barrier(0);
;     g8_compute<1, 2>(acc, L + (kb & 1) * 32768, wm, wn, lane);
;   }
	s_setprio 1
	s_waitcnt lgkmcnt(3)
	v_mfma_f32_16x16x32_bf16 v[158:161], v[226:229], v[192:195], v[158:161]
	s_waitcnt lgkmcnt(2)
	v_mfma_f32_16x16x32_bf16 v[154:157], v[230:233], v[192:195], v[154:157]
	s_waitcnt lgkmcnt(1)
	v_mfma_f32_16x16x32_bf16 v[150:153], v[234:237], v[192:195], v[150:153]
	s_waitcnt lgkmcnt(0)
	s_waitcnt vmcnt(7)
	ds_write_b128 v246, v[14:17] offset:32768
	s_waitcnt vmcnt(6)
	ds_write_b128 v246, v[2:5] offset:40960
	s_waitcnt vmcnt(5)
	ds_write_b128 v246, v[6:9] offset:49152
	s_waitcnt vmcnt(4)
	ds_write_b128 v246, v[10:13] offset:57344
	v_lshl_add_u64 v[2:3], v[176:177], 0, s[0:1]
	v_lshl_add_u64 v[4:5], v[174:175], 0, s[0:1]
	v_lshl_add_u64 v[6:7], v[172:173], 0, s[0:1]
	v_lshl_add_u64 v[10:11], v[170:171], 0, s[0:1]
	global_load_dwordx4 v[14:17], v[2:3], off
	s_nop 0
	global_load_dwordx4 v[2:5], v[4:5], off
	s_nop 0
	global_load_dwordx4 v[6:9], v[6:7], off
	s_nop 0
	global_load_dwordx4 v[10:13], v[10:11], off
	v_mfma_f32_16x16x32_bf16 v[146:149], v[238:241], v[192:195], v[146:149]
	v_mfma_f32_16x16x32_bf16 v[142:145], v[226:229], v[198:201], v[142:145]
	v_mfma_f32_16x16x32_bf16 v[138:141], v[230:233], v[198:201], v[138:141]
	v_mfma_f32_16x16x32_bf16 v[134:137], v[234:237], v[198:201], v[134:137]
	v_mfma_f32_16x16x32_bf16 v[130:133], v[238:241], v[198:201], v[130:133]
	v_mfma_f32_16x16x32_bf16 v[126:129], v[226:229], v[202:205], v[126:129]
	v_mfma_f32_16x16x32_bf16 v[122:125], v[230:233], v[202:205], v[122:125]
	v_mfma_f32_16x16x32_bf16 v[118:121], v[234:237], v[202:205], v[118:121]
	v_mfma_f32_16x16x32_bf16 v[114:117], v[238:241], v[202:205], v[114:117]
	v_mfma_f32_16x16x32_bf16 v[110:113], v[226:229], v[206:209], v[110:113]
	v_mfma_f32_16x16x32_bf16 v[106:109], v[230:233], v[206:209], v[106:109]
	v_mfma_f32_16x16x32_bf16 v[102:105], v[234:237], v[206:209], v[102:105]
	v_mfma_f32_16x16x32_bf16 v[98:101], v[238:241], v[206:209], v[98:101]
	v_mfma_f32_16x16x32_bf16 v[94:97], v[226:229], v[210:213], v[94:97]
	v_mfma_f32_16x16x32_bf16 v[90:93], v[230:233], v[210:213], v[90:93]
	v_mfma_f32_16x16x32_bf16 v[86:89], v[234:237], v[210:213], v[86:89]
	v_mfma_f32_16x16x32_bf16 v[82:85], v[238:241], v[210:213], v[82:85]
	v_mfma_f32_16x16x32_bf16 v[78:81], v[226:229], v[214:217], v[78:81]
	v_mfma_f32_16x16x32_bf16 v[74:77], v[230:233], v[214:217], v[74:77]
	v_mfma_f32_16x16x32_bf16 v[70:73], v[234:237], v[214:217], v[70:73]
	v_mfma_f32_16x16x32_bf16 v[66:69], v[238:241], v[214:217], v[66:69]
	v_mfma_f32_16x16x32_bf16 v[62:65], v[226:229], v[218:221], v[62:65]
	v_mfma_f32_16x16x32_bf16 v[58:61], v[230:233], v[218:221], v[58:61]
	v_mfma_f32_16x16x32_bf16 v[54:57], v[234:237], v[218:221], v[54:57]
	v_mfma_f32_16x16x32_bf16 v[50:53], v[238:241], v[218:221], v[50:53]
	v_mfma_f32_16x16x32_bf16 v[46:49], v[226:229], v[222:225], v[46:49]
	v_mfma_f32_16x16x32_bf16 v[42:45], v[230:233], v[222:225], v[42:45]
	v_mfma_f32_16x16x32_bf16 v[38:41], v[234:237], v[222:225], v[38:41]
	v_mfma_f32_16x16x32_bf16 v[34:37], v[238:241], v[222:225], v[34:37]
	s_setprio 0
	s_branch .Lstg_942_b
.Lstg_942_b2:
	s_waitcnt vmcnt(7)
	ds_write_b128 v246, v[14:17] offset:32768
	s_waitcnt vmcnt(6)
	ds_write_b128 v246, v[2:5] offset:40960
	s_waitcnt vmcnt(5)
	ds_write_b128 v246, v[6:9] offset:49152
	s_waitcnt vmcnt(4)
	ds_write_b128 v246, v[10:13] offset:57344
	v_lshl_add_u64 v[2:3], v[176:177], 0, s[0:1]
	v_lshl_add_u64 v[4:5], v[174:175], 0, s[0:1]
	v_lshl_add_u64 v[6:7], v[172:173], 0, s[0:1]
	v_lshl_add_u64 v[10:11], v[170:171], 0, s[0:1]
	global_load_dwordx4 v[14:17], v[2:3], off
	s_nop 0
	global_load_dwordx4 v[2:5], v[4:5], off
	s_nop 0
	global_load_dwordx4 v[6:9], v[6:7], off
	s_nop 0
	global_load_dwordx4 v[10:13], v[10:11], off

; DI f32x4 mfma16(bf16x8 a, bf16x8 b, f32x4 c) { return __builtin_amdgcn_mfma_f32_16x16x32_bf16(a, b, c, 0, 0, 0); }
; #pragma unroll
;   for (int ks = KS0; ks < KS1; ++ks) {
;     bf16x8 af[8], bfr[4];
; #pragma unroll
;     for (int i = 0; i < 8; ++i) {
;       const int r = wm * 128 + i * 16 + (lane & 15);
;       af[i] = *(const bf16x8*)(S + r * 64 + (((ks * 4 + (lane >> 4)) ^ ((r >> 1) & 7)) << 3));
;     }
; #pragma unroll
;     for (int j = 0; j < 4; ++j) {
;       const int r = wn * 64 + j * 16 + (lane & 15);
;       bfr[j] = *(const bf16x8*)(S + 16384 + r * 64 + (((ks * 4 + (lane >> 4)) ^ ((r >> 1) & 7)) << 3));
;     }
;     __builtin_amdgcn_s_setprio(1);
; #pragma unroll
;     for (int i = 0; i < 8; ++i)
; #pragma unroll
;       for (int j = 0; j < 4; ++j) acc[i][j] = mfma16(bfr[j], af[i], acc[i][j]);
;     __builtin_amdgcn_s_setprio(0);
;   }
; }
; DI void gemm8_accum(f32x4 (&acc)[8][4], const bf16_t* a, size_t lda, const bf16_t* b, size_t ldb, int nkb, bf16_t* L,
;                     const bool pre, const bf16_t* an, size_t ldan, const bf16_t* bn, size_t ldbn) {
;     ...
;   for (int kb = 0; kb + 2 < nkb; ++kb) {
;     __syncthreads();
;     g8_store1(L + ((kb + 1) & 1) * 32768, ra, lrow, lch);
;     g8_load1o(ra, a + (kb + 2) * 64, offa);
;     __builtin_amdgcn_sched_barrier(0);
;     g8_compute<0, 1>(acc, L + (kb & 1) * 32768, wm, wn, lane);
;     __builtin_amdgcn_sched_barrier(0);
;     g8_store1(L + ((kb + 1) & 1) * 32768 + 16384, rb, lrow, lch);
;     g8_load1o(rb, b + (kb + 2) * 64, offb);
;     __builtin_amdgcn_sched_barrier(0);
;     g8_compute<1, 2>(acc, L + (kb & 1) * 32768, wm, wn, lane);
;   }
.LBB0_1007:
	s_add_i32 s3, s2, 0x8000
	s_and_b32 s4, s3, 0x8000
	v_lshl_add_u32 v0, s4, 1, v163
	v_lshl_add_u32 v246, s4, 1, v163
	s_waitcnt lgkmcnt(0)
	s_barrier
	s_cmp_eq_u32 s100, 0
	s_cbranch_scc1 .Lstg_1007_a
	s_setprio 1
	v_mfma_f32_16x16x32_bf16 v[158:161], v[226:229], v[192:195], v[158:161]
	v_mfma_f32_16x16x32_bf16 v[154:157], v[230:233], v[192:195], v[154:157]
	v_mfma_f32_16x16x32_bf16 v[150:153], v[234:237], v[192:195], v[150:153]
	v_mfma_f32_16x16x32_bf16 v[146:149], v[238:241], v[192:195], v[146:149]
	v_mfma_f32_16x16x32_bf16 v[142:145], v[226:229], v[198:201], v[142:145]
	v_mfma_f32_16x16x32_bf16 v[138:141], v[230:233], v[198:201], v[138:141]
	v_mfma_f32_16x16x32_bf16 v[134:137], v[234:237], v[198:201], v[134:137]
	v_mfma_f32_16x16x32_bf16 v[130:133], v[238:241], v[198:201], v[130:133]
	v_mfma_f32_16x16x32_bf16 v[126:129], v[226:229], v[202:205], v[126:129]
	v_mfma_f32_16x16x32_bf16 v[122:125], v[230:233], v[202:205], v[122:125]
	v_mfma_f32_16x16x32_bf16 v[118:121], v[234:237], v[202:205], v[118:121]
	v_mfma_f32_16x16x32_bf16 v[114:117], v[238:241], v[202:205], v[114:117]
	v_mfma_f32_16x16x32_bf16 v[110:113], v[226:229], v[206:209], v[110:113]
	v_mfma_f32_16x16x32_bf16 v[106:109], v[230:233], v[206:209], v[106:109]
	v_mfma_f32_16x16x32_bf16 v[102:105], v[234:237], v[206:209], v[102:105]
	v_mfma_f32_16x16x32_bf16 v[98:101], v[238:241], v[206:209], v[98:101]
	v_mfma_f32_16x16x32_bf16 v[90:93], v[226:229], v[210:213], v[90:93]
	v_mfma_f32_16x16x32_bf16 v[86:89], v[230:233], v[210:213], v[86:89]
	v_mfma_f32_16x16x32_bf16 v[82:85], v[234:237], v[210:213], v[82:85]
	v_mfma_f32_16x16x32_bf16 v[78:81], v[238:241], v[210:213], v[78:81]
	v_mfma_f32_16x16x32_bf16 v[74:77], v[226:229], v[214:217], v[74:77]
	v_mfma_f32_16x16x32_bf16 v[70:73], v[230:233], v[214:217], v[70:73]
	v_mfma_f32_16x16x32_bf16 v[66:69], v[234:237], v[214:217], v[66:69]
	v_mfma_f32_16x16x32_bf16 v[62:65], v[238:241], v[214:217], v[62:65]
	v_mfma_f32_16x16x32_bf16 v[58:61], v[226:229], v[218:221], v[58:61]
	v_mfma_f32_16x16x32_bf16 v[50:53], v[230:233], v[218:221], v[50:53]
	v_mfma_f32_16x16x32_bf16 v[46:49], v[234:237], v[218:221], v[46:49]
	v_mfma_f32_16x16x32_bf16 v[38:41], v[238:241], v[218:221], v[38:41]
	v_mfma_f32_16x16x32_bf16 v[30:33], v[226:229], v[222:225], v[30:33]
	v_mfma_f32_16x16x32_bf16 v[26:29], v[230:233], v[222:225], v[26:29]
	v_mfma_f32_16x16x32_bf16 v[22:25], v[234:237], v[222:225], v[22:25]
	v_mfma_f32_16x16x32_bf16 v[18:21], v[238:241], v[222:225], v[18:21]
	s_setprio 0
.Lstg_1007_a:
	s_and_b32 s2, s2, 0x8000
	s_lshl_b32 s2, s2, 1
	s_add_i32 s2, s2, 0
	v_lshl_add_u32 v191, v186, 1, s2
	v_add_u32_e32 v222, v191, v181
	ds_read_b128 v[192:195], v222
	ds_read_b128 v[198:201], v222 offset:2048
	ds_read_b128 v[202:205], v222 offset:4096
	ds_read_b128 v[206:209], v222 offset:6144
	ds_read_b128 v[210:213], v222 offset:8192
	ds_read_b128 v[214:217], v222 offset:10240
	ds_read_b128 v[218:221], v222 offset:12288
	ds_read_b128 v[222:225], v222 offset:14336
	v_add_u32_e32 v191, v191, v180
	ds_read_b128 v[226:229], v191 offset:32768
	ds_read_b128 v[230:233], v191 offset:34816
	ds_read_b128 v[234:237], v191 offset:36864
	ds_read_b128 v[238:241], v191 offset:38912
	s_setprio 1
	s_waitcnt lgkmcnt(3)
	v_mfma_f32_16x16x32_bf16 v[158:161], v[226:229], v[192:195], v[158:161]
	s_waitcnt lgkmcnt(2)
	v_mfma_f32_16x16x32_bf16 v[154:157], v[230:233], v[192:195], v[154:157]
	s_waitcnt lgkmcnt(1)
	v_mfma_f32_16x16x32_bf16 v[150:153], v[234:237], v[192:195], v[150:153]
	s_waitcnt lgkmcnt(0)
	s_waitcnt vmcnt(7)
	ds_write_b128 v0, v[34:37]
	s_waitcnt vmcnt(6)
	ds_write_b128 v0, v[42:45] offset:8192
	s_waitcnt vmcnt(5)
	ds_write_b128 v0, v[54:57] offset:16384
	s_waitcnt vmcnt(4)
	ds_write_b128 v0, v[94:97] offset:24576
	v_lshl_add_u64 v[34:35], v[178:179], 0, s[0:1]
	v_lshl_add_u64 v[42:43], v[176:177], 0, s[0:1]
	v_lshl_add_u64 v[54:55], v[174:175], 0, s[0:1]
	v_lshl_add_u64 v[94:95], v[172:173], 0, s[0:1]
	global_load_dwordx4 v[34:37], v[34:35], off
	s_nop 0
	global_load_dwordx4 v[42:45], v[42:43], off
	s_nop 0
	global_load_dwordx4 v[54:57], v[54:55], off
	s_nop 0
	global_load_dwordx4 v[94:97], v[94:95], off
	v_mfma_f32_16x16x32_bf16 v[146:149], v[238:241], v[192:195], v[146:149]
	v_mfma_f32_16x16x32_bf16 v[142:145], v[226:229], v[198:201], v[142:145]
	v_mfma_f32_16x16x32_bf16 v[138:141], v[230:233], v[198:201], v[138:141]
	v_mfma_f32_16x16x32_bf16 v[134:137], v[234:237], v[198:201], v[134:137]
	v_mfma_f32_16x16x32_bf16 v[130:133], v[238:241], v[198:201], v[130:133]
	v_mfma_f32_16x16x32_bf16 v[126:129], v[226:229], v[202:205], v[126:129]
	v_mfma_f32_16x16x32_bf16 v[122:125], v[230:233], v[202:205], v[122:125]
	v_mfma_f32_16x16x32_bf16 v[118:121], v[234:237], v[202:205], v[118:121]
	v_mfma_f32_16x16x32_bf16 v[114:117], v[238:241], v[202:205], v[114:117]
	v_mfma_f32_16x16x32_bf16 v[110:113], v[226:229], v[206:209], v[110:113]
	v_mfma_f32_16x16x32_bf16 v[106:109], v[230:233], v[206:209], v[106:109]
	v_mfma_f32_16x16x32_bf16 v[102:105], v[234:237], v[206:209], v[102:105]
	v_mfma_f32_16x16x32_bf16 v[98:101], v[238:241], v[206:209], v[98:101]
	v_mfma_f32_16x16x32_bf16 v[90:93], v[226:229], v[210:213], v[90:93]
	v_mfma_f32_16x16x32_bf16 v[86:89], v[230:233], v[210:213], v[86:89]
	v_mfma_f32_16x16x32_bf16 v[82:85], v[234:237], v[210:213], v[82:85]
	v_mfma_f32_16x16x32_bf16 v[78:81], v[238:241], v[210:213], v[78:81]
	v_mfma_f32_16x16x32_bf16 v[74:77], v[226:229], v[214:217], v[74:77]
	v_mfma_f32_16x16x32_bf16 v[70:73], v[230:233], v[214:217], v[70:73]
	v_mfma_f32_16x16x32_bf16 v[66:69], v[234:237], v[214:217], v[66:69]
	v_mfma_f32_16x16x32_bf16 v[62:65], v[238:241], v[214:217], v[62:65]
	v_mfma_f32_16x16x32_bf16 v[58:61], v[226:229], v[218:221], v[58:61]
	v_mfma_f32_16x16x32_bf16 v[50:53], v[230:233], v[218:221], v[50:53]
	v_mfma_f32_16x16x32_bf16 v[46:49], v[234:237], v[218:221], v[46:49]
	v_mfma_f32_16x16x32_bf16 v[38:41], v[238:241], v[218:221], v[38:41]
	v_mfma_f32_16x16x32_bf16 v[30:33], v[226:229], v[222:225], v[30:33]
	v_mfma_f32_16x16x32_bf16 v[26:29], v[230:233], v[222:225], v[26:29]
	v_mfma_f32_16x16x32_bf16 v[22:25], v[234:237], v[222:225], v[22:25]
	v_mfma_f32_16x16x32_bf16 v[18:21], v[238:241], v[222:225], v[18:21]
	s_setprio 0
	v_lshl_add_u32 v0, v182, 1, s2
	v_add_u32_e32 v191, v0, v181
	ds_read_b128 v[192:195], v191
	ds_read_b128 v[198:201], v191 offset:2048
	ds_read_b128 v[202:205], v191 offset:4096
	ds_read_b128 v[206:209], v191 offset:6144
	ds_read_b128 v[210:213], v191 offset:8192
	ds_read_b128 v[214:217], v191 offset:10240
	ds_read_b128 v[218:221], v191 offset:12288
	ds_read_b128 v[222:225], v191 offset:14336
	v_add_u32_e32 v0, v0, v180
	ds_read_b128 v[226:229], v0 offset:32768
	ds_read_b128 v[230:233], v0 offset:34816
	ds_read_b128 v[234:237], v0 offset:36864
	ds_read_b128 v[238:241], v0 offset:38912
	s_cmp_lg_u32 s101, 0
	s_cbranch_scc1 .Lstg_1007_b2
; DI f32x4 mfma16(bf16x8 a, bf16x8 b, f32x4 c) { return __builtin_amdgcn_mfma_f32_16x16x32_bf16(a, b, c, 0, 0, 0); }
; #pragma unroll
;   for (int ks = KS0; ks < KS1; ++ks) {
;     bf16x8 af[8], bfr[4];
; #pragma unroll
;     for (int i = 0; i < 8; ++i) {
;       const int r = wm * 128 + i * 16 + (lane & 15);
;       af[i] = *(const bf16x8*)(S + r * 64 + (((ks * 4 + (lane >> 4)) ^ ((r >> 1) & 7)) << 3));
;     }
; #pragma unroll
;     for (int j = 0; j < 4; ++j) {
;       const int r = wn * 64 + j * 16 + (lane & 15);
;       bfr[j] = *(const bf16x8*)(S + 16384 + r * 64 + (((ks * 4 + (lane >> 4)) ^ ((r >> 1) & 7)) << 3));
;     }
;     __builtin_amdgcn_s_setprio(1);
; #pragma unroll
;     for (int i = 0; i < 8; ++i)
; #pragma unroll
;       for (int j = 0; j < 4; ++j) acc[i][j] = mfma16(bfr[j], af[i], acc[i][j]);
;     __builtin_amdgcn_s_setprio(0);
;   }
; }
; DI void gemm8_accum(f32x4 (&acc)[8][4], const bf16_t* a, size_t lda, const bf16_t* b, size_t ldb, int nkb, bf16_t* L,
;                     const bool pre, const bf16_t* an, size_t ldan, const bf16_t* bn, size_t ldbn) {
;     ...
;   for (int kb = 0; kb + 2 < nkb; ++kb) {
;     __syncthreads();
;     g8_store1(L + ((kb + 1) & 1) * 32768, ra, lrow, lch);
;     g8_load1o(ra, a + (kb + 2) * 64, offa);
;     __builtin_amdgcn_sched_barrier(0);
;     g8_compute<0, 1>(acc, L + (kb & 1) * 32768, wm, wn, lane);
;     __builtin_amdgcn_sched_barrier(0);
;     g8_store1(L + ((kb + 1) & 1) * 32768 + 16384, rb, lrow, lch);
;     g8_load1o(rb, b + (kb + 2) * 64, offb);
;     __builtin_amdgcn_sched_barrier(0);
;     g8_compute<1, 2>(acc, L + (kb & 1) * 32768, wm, wn, lane);
;   }
	s_setprio 1
	s_waitcnt lgkmcnt(3)
	v_mfma_f32_16x16x32_bf16 v[158:161], v[226:229], v[192:195], v[158:161]
	s_waitcnt lgkmcnt(2)
	v_mfma_f32_16x16x32_bf16 v[154:157], v[230:233], v[192:195], v[154:157]
	s_waitcnt lgkmcnt(1)
	v_mfma_f32_16x16x32_bf16 v[150:153], v[234:237], v[192:195], v[150:153]
	s_waitcnt lgkmcnt(0)
	s_waitcnt vmcnt(7)
	ds_write_b128 v246, v[14:17] offset:32768
	s_waitcnt vmcnt(6)
	ds_write_b128 v246, v[2:5] offset:40960
	s_waitcnt vmcnt(5)
	ds_write_b128 v246, v[6:9] offset:49152
	s_waitcnt vmcnt(4)
	ds_write_b128 v246, v[10:13] offset:57344
	v_lshl_add_u64 v[2:3], v[170:171], 0, s[0:1]
	v_lshl_add_u64 v[4:5], v[168:169], 0, s[0:1]
	v_lshl_add_u64 v[6:7], v[166:167], 0, s[0:1]
	v_lshl_add_u64 v[10:11], v[164:165], 0, s[0:1]
	global_load_dwordx4 v[14:17], v[2:3], off
	s_nop 0
	global_load_dwordx4 v[2:5], v[4:5], off
	s_nop 0
	global_load_dwordx4 v[6:9], v[6:7], off
	s_nop 0
	global_load_dwordx4 v[10:13], v[10:11], off
	v_mfma_f32_16x16x32_bf16 v[146:149], v[238:241], v[192:195], v[146:149]
	v_mfma_f32_16x16x32_bf16 v[142:145], v[226:229], v[198:201], v[142:145]
	v_mfma_f32_16x16x32_bf16 v[138:141], v[230:233], v[198:201], v[138:141]
	v_mfma_f32_16x16x32_bf16 v[134:137], v[234:237], v[198:201], v[134:137]
	v_mfma_f32_16x16x32_bf16 v[130:133], v[238:241], v[198:201], v[130:133]
	v_mfma_f32_16x16x32_bf16 v[126:129], v[226:229], v[202:205], v[126:129]
	v_mfma_f32_16x16x32_bf16 v[122:125], v[230:233], v[202:205], v[122:125]
	v_mfma_f32_16x16x32_bf16 v[118:121], v[234:237], v[202:205], v[118:121]
	v_mfma_f32_16x16x32_bf16 v[114:117], v[238:241], v[202:205], v[114:117]
	v_mfma_f32_16x16x32_bf16 v[110:113], v[226:229], v[206:209], v[110:113]
	v_mfma_f32_16x16x32_bf16 v[106:109], v[230:233], v[206:209], v[106:109]
	v_mfma_f32_16x16x32_bf16 v[102:105], v[234:237], v[206:209], v[102:105]
	v_mfma_f32_16x16x32_bf16 v[98:101], v[238:241], v[206:209], v[98:101]
	v_mfma_f32_16x16x32_bf16 v[90:93], v[226:229], v[210:213], v[90:93]
	v_mfma_f32_16x16x32_bf16 v[86:89], v[230:233], v[210:213], v[86:89]
	v_mfma_f32_16x16x32_bf16 v[82:85], v[234:237], v[210:213], v[82:85]
	v_mfma_f32_16x16x32_bf16 v[78:81], v[238:241], v[210:213], v[78:81]
	v_mfma_f32_16x16x32_bf16 v[74:77], v[226:229], v[214:217], v[74:77]
	v_mfma_f32_16x16x32_bf16 v[70:73], v[230:233], v[214:217], v[70:73]
	v_mfma_f32_16x16x32_bf16 v[66:69], v[234:237], v[214:217], v[66:69]
	v_mfma_f32_16x16x32_bf16 v[62:65], v[238:241], v[214:217], v[62:65]
	v_mfma_f32_16x16x32_bf16 v[58:61], v[226:229], v[218:221], v[58:61]
	v_mfma_f32_16x16x32_bf16 v[50:53], v[230:233], v[218:221], v[50:53]
	v_mfma_f32_16x16x32_bf16 v[46:49], v[234:237], v[218:221], v[46:49]
	v_mfma_f32_16x16x32_bf16 v[38:41], v[238:241], v[218:221], v[38:41]
	v_mfma_f32_16x16x32_bf16 v[30:33], v[226:229], v[222:225], v[30:33]
	v_mfma_f32_16x16x32_bf16 v[26:29], v[230:233], v[222:225], v[26:29]
	v_mfma_f32_16x16x32_bf16 v[22:25], v[234:237], v[222:225], v[22:25]
	v_mfma_f32_16x16x32_bf16 v[18:21], v[238:241], v[222:225], v[18:21]
	s_setprio 0
	s_branch .Lstg_1007_b
.Lstg_1007_b2:
	s_waitcnt vmcnt(7)
	ds_write_b128 v246, v[14:17] offset:32768
	s_waitcnt vmcnt(6)
	ds_write_b128 v246, v[2:5] offset:40960
	s_waitcnt vmcnt(5)
	ds_write_b128 v246, v[6:9] offset:49152
	s_waitcnt vmcnt(4)
	ds_write_b128 v246, v[10:13] offset:57344
	v_lshl_add_u64 v[2:3], v[170:171], 0, s[0:1]
	v_lshl_add_u64 v[4:5], v[168:169], 0, s[0:1]
	v_lshl_add_u64 v[6:7], v[166:167], 0, s[0:1]
	v_lshl_add_u64 v[10:11], v[164:165], 0, s[0:1]
	global_load_dwordx4 v[14:17], v[2:3], off
	s_nop 0
	global_load_dwordx4 v[2:5], v[4:5], off
	s_nop 0
	global_load_dwordx4 v[6:9], v[6:7], off
	s_nop 0
	global_load_dwordx4 v[10:13], v[10:11], off
